# gate buffer G and intermediate T stored tile-major (1 KiB contiguous per access instruction) between P4/P6a/P6b epilogues
# speedup vs baseline: 1.0051x; 1.0051x over previous
; __device__ __forceinline__ unsigned cvt_pk_bf16(float lo, float hi) { typedef float f2_t __attribute__((ext_vector_type(2))); typedef __bf16 b2_t __attribute__((ext_vector_type(2))); const f2_t v = {lo, hi}; return __builtin_bit_cast(unsigned, __builtin_convertvector(v, b2_t)); }
; __device__ __forceinline__ float sigm(float x) { return __builtin_amdgcn_rcpf(1.0f + __builtin_amdgcn_exp2f(-1.4426950409f * x)); }
; __device__ __forceinline__ float gelu_tanh_f(float x) { return x * sigm(1.5957691216f * (x + 0.044715f * x * x * x)); }
;     template <int MODE> __device__ __forceinline__ void body(const f32x4 (&acc)[2][2][4][2], bf16_t* base, int ld, int row0, int cin, int rl0, int fq, const float* bp, float* sbase) const {
;     ...
;         for (int ai = 0; ai < 2; ++ai)
; #pragma unroll
;             for (int m = 0; m < 4; ++m) {
;                 bf16_t* rowp = base + (size_t)(row0 + ai * HALF + m * 16) * ld + cin;
;                 const float rsv = rs[ai * HALF + rl0 + m * 16];
;                 float s1 = 0.f, s2 = 0.f;
; #pragma unroll
;                 for (int bj = 0; bj < 2; ++bj) {
;                     f32x4 v0 = acc[ai][bj][m][0] * rsv + bv[bj][0], v1 = acc[ai][bj][m][1] * rsv + bv[bj][1];
;                     if (MODE == 1 || MODE == 2) {
; #pragma unroll
;                         for (int e = 0; e < 4; ++e) { v0[e] = gelu_tanh_f(v0[e]); v1[e] = gelu_tanh_f(v1[e]); }
;                     } else if (MODE == 3) {
; #pragma unroll
;                         for (int e = 0; e < 4; ++e) { v0[e] = sigm(v0[e]); v1[e] = sigm(v1[e]); }
;                     }
;                     if (MODE == 2) {
; #pragma unroll
;                         for (int e = 0; e < 4; ++e) { s1 += v0[e] + v1[e]; s2 += v0[e] * v0[e] + v1[e] * v1[e]; }
;                     }
;                     u32x4 w; w.x = cvt_pk_bf16(v0[0], v0[1]); w.y = cvt_pk_bf16(v0[2], v0[3]); w.z = cvt_pk_bf16(v1[0], v1[1]); w.w = cvt_pk_bf16(v1[2], v1[3]);
;                     *(u32x4*)(rowp + bj * HALF) = w;
.LBB0_274:
	s_cmp_gt_u32 s7, 5
	s_cbranch_scc0 .LBB0_286
	s_cmp_gt_u32 s7, 9
	s_cbranch_scc0 .LBB0_283
	s_cmp_gt_u32 s7, 13
	s_cbranch_scc0 .LBB0_278
	v_mov_b32_e32 v205, s7
	v_add_u32_e32 v205, -14, v205
	v_lshlrev_b32_e32 v205, 17, v205
	v_lshl_add_u32 v205, s64, 21, v205
	v_lshrrev_b32_e32 v201, 6, v189
	v_lshl_add_u32 v205, v201, 14, v205
	v_lshl_add_u32 v201, v188, 4, v205
	v_add_u32_e32 v202, 0x1000, v201
	v_add_u32_e32 v203, 0x2000, v201
	v_add_u32_e32 v204, 0x3000, v201
	s_lshl_b32 s1, s7, 8
	s_add_i32 s76, s1, 0xfffff200
	s_lshl_b64 s[2:3], s[76:77], 1
	s_add_u32 s2, s70, s2
	v_readlane_b32 s48, v254, 23
	s_addc_u32 s3, s71, s3
	s_lshl_b64 s[8:9], s[76:77], 2
	v_readlane_b32 s62, v254, 37
	v_readlane_b32 s63, v254, 38
	s_add_u32 s8, s62, s8
	s_addc_u32 s9, s63, s9
	v_ashrrev_i32_e32 v153, 31, v152
	v_lshl_add_u64 v[132:133], v[152:153], 2, s[8:9]
	global_load_dwordx4 v[136:139], v[132:133], off offset:16
	global_load_dwordx4 v[140:143], v[132:133], off
	global_load_dwordx4 v[128:131], v[132:133], off offset:528
	s_nop 0
	global_load_dwordx4 v[132:135], v[132:133], off offset:512
	v_ashrrev_i32_e32 v151, 31, v150
	v_lshlrev_b64 v[156:157], 13, v[150:151]
	v_lshl_add_u32 v151, v200, 2, 0
	v_lshl_add_u64 v[154:155], v[152:153], 1, s[2:3]
	v_add_u32_e32 v149, 0x20800, v151
	v_lshl_add_u64 v[154:155], v[154:155], 0, v[156:157]
	ds_read2_b32 v[156:157], v149 offset1:16
	s_mov_b64 s[2:3], 0x20000
	s_mov_b32 s1, 0x60000
	v_add_u32_e32 v151, 0x20a00, v151
	v_readlane_b32 s49, v254, 24
	v_readlane_b32 s50, v254, 25
	v_readlane_b32 s51, v254, 26
	v_readlane_b32 s52, v254, 27
	v_readlane_b32 s53, v254, 28
	v_readlane_b32 s54, v254, 29
	v_readlane_b32 s55, v254, 30
	v_readlane_b32 s56, v254, 31
	v_readlane_b32 s57, v254, 32
	v_readlane_b32 s58, v254, 33
	v_readlane_b32 s59, v254, 34
	v_readlane_b32 s60, v254, 35
	v_readlane_b32 s61, v254, 36
	s_mov_b64 s[52:53], 0x50000
	s_mov_b64 s[54:55], 0x58000
	s_mov_b64 s[50:51], 0x48000
	s_mov_b64 s[48:49], 0x18000
	s_mov_b64 s[42:43], 0
	s_waitcnt vmcnt(3) lgkmcnt(0)
	v_pk_fma_f32 v[162:163], v[114:115], v[156:157], v[138:139] op_sel_hi:[1,0,1]
	s_waitcnt vmcnt(2)
	v_pk_fma_f32 v[158:159], v[118:119], v[156:157], v[142:143] op_sel_hi:[1,0,1]
	v_pk_fma_f32 v[160:161], v[116:117], v[156:157], v[140:141] op_sel_hi:[1,0,1]
	v_mul_f32_e32 v158, 0xbfb8aa3b, v158
	v_exp_f32_e32 v158, v158
	v_pk_fma_f32 v[164:165], v[112:113], v[156:157], v[136:137] op_sel_hi:[1,0,1]
	v_mul_f32_e32 v153, 0xbfb8aa3b, v160
	v_mul_f32_e32 v160, 0xbfb8aa3b, v164
	v_add_f32_e32 v158, 1.0, v158
	v_mul_f32_e32 v164, 0xbfb8aa3b, v165
	v_rcp_f32_e32 v165, v158
	v_mul_f32_e32 v158, 0xbfb8aa3b, v162
	v_exp_f32_e32 v158, v158
	v_mul_f32_e32 v161, 0xbfb8aa3b, v161
	v_exp_f32_e32 v153, v153
	v_exp_f32_e32 v160, v160
	v_add_f32_e32 v158, 1.0, v158
	v_rcp_f32_e32 v162, v158
	v_mul_f32_e32 v158, 0xbfb8aa3b, v159
	v_exp_f32_e32 v158, v158
	v_exp_f32_e32 v161, v161
	v_exp_f32_e32 v164, v164
	v_add_f32_e32 v153, 1.0, v153
	v_add_f32_e32 v158, 1.0, v158
	v_rcp_f32_e32 v159, v158
	v_mul_f32_e32 v158, 0xbfb8aa3b, v163
	v_exp_f32_e32 v158, v158
	v_add_f32_e32 v160, 1.0, v160
	v_add_f32_e32 v161, 1.0, v161
	v_add_f32_e32 v164, 1.0, v164
	v_add_f32_e32 v158, 1.0, v158
	v_rcp_f32_e32 v153, v153
	v_rcp_f32_e32 v160, v160
	v_rcp_f32_e32 v161, v161
	v_rcp_f32_e32 v164, v164
	v_rcp_f32_e32 v163, v158
	v_cvt_pk_bf16_f32 v159, v165, v159
	v_cvt_pk_bf16_f32 v158, v153, v161
	v_cvt_pk_bf16_f32 v160, v160, v164
	v_cvt_pk_bf16_f32 v161, v162, v163
	global_store_dwordx4 v201, v[158:161], s[70:71]
	s_waitcnt vmcnt(2)
	v_pk_fma_f32 v[162:163], v[122:123], v[156:157], v[130:131] op_sel_hi:[1,0,1]
	v_pk_fma_f32 v[164:165], v[120:121], v[156:157], v[128:129] op_sel_hi:[1,0,1]
	s_waitcnt vmcnt(1)
	v_pk_fma_f32 v[158:159], v[126:127], v[156:157], v[134:135] op_sel_hi:[1,0,1]
	v_pk_fma_f32 v[160:161], v[124:125], v[156:157], v[132:133] op_sel_hi:[1,0,1]
	v_mul_f32_e32 v158, 0xbfb8aa3b, v158
	v_exp_f32_e32 v158, v158
	v_mul_f32_e32 v156, 0xbfb8aa3b, v164
	v_mul_f32_e32 v153, 0xbfb8aa3b, v160
	v_mul_f32_e32 v160, 0xbfb8aa3b, v161
	v_add_f32_e32 v158, 1.0, v158
	v_rcp_f32_e32 v164, v158
	v_mul_f32_e32 v158, 0xbfb8aa3b, v162
	v_exp_f32_e32 v158, v158
	v_mul_f32_e32 v161, 0xbfb8aa3b, v165
	v_exp_f32_e32 v153, v153
	v_exp_f32_e32 v156, v156
	v_add_f32_e32 v158, 1.0, v158
	v_rcp_f32_e32 v162, v158
	v_mul_f32_e32 v158, 0xbfb8aa3b, v159
	v_exp_f32_e32 v158, v158
	v_exp_f32_e32 v160, v160
	v_exp_f32_e32 v161, v161
	v_add_f32_e32 v153, 1.0, v153
	v_add_f32_e32 v158, 1.0, v158
	v_rcp_f32_e32 v159, v158
	v_mul_f32_e32 v158, 0xbfb8aa3b, v163
	v_exp_f32_e32 v158, v158
	v_add_f32_e32 v156, 1.0, v156
	v_add_f32_e32 v160, 1.0, v160
	v_add_f32_e32 v161, 1.0, v161
	v_add_f32_e32 v158, 1.0, v158
	v_rcp_f32_e32 v153, v153
	v_rcp_f32_e32 v156, v156
	v_rcp_f32_e32 v160, v160
	v_rcp_f32_e32 v161, v161
	v_rcp_f32_e32 v163, v158
	v_cvt_pk_bf16_f32 v159, v164, v159
	v_cvt_pk_bf16_f32 v158, v153, v160
	v_cvt_pk_bf16_f32 v160, v156, v161
	v_cvt_pk_bf16_f32 v161, v162, v163
	v_mov_b32_e32 v156, v157
	global_store_dwordx4 v201, v[158:161], s[70:71] offset:1024
	v_pk_fma_f32 v[164:165], v[98:99], v[156:157], v[138:139] op_sel_hi:[1,0,1]
	v_pk_fma_f32 v[166:167], v[96:97], v[156:157], v[136:137] op_sel_hi:[1,0,1]
	v_pk_fma_f32 v[160:161], v[102:103], v[156:157], v[142:143] op_sel_hi:[1,0,1]
	v_pk_fma_f32 v[162:163], v[100:101], v[156:157], v[140:141] op_sel_hi:[1,0,1]
	v_mul_f32_e32 v160, 0xbfb8aa3b, v160
	v_exp_f32_e32 v160, v160
	v_mul_f32_e32 v157, 0xbfb8aa3b, v166
	v_mul_f32_e32 v153, 0xbfb8aa3b, v162
	v_mul_f32_e32 v162, 0xbfb8aa3b, v163
	v_add_f32_e32 v160, 1.0, v160
	v_rcp_f32_e32 v166, v160
; __device__ __forceinline__ unsigned cvt_pk_bf16(float lo, float hi) { typedef float f2_t __attribute__((ext_vector_type(2))); typedef __bf16 b2_t __attribute__((ext_vector_type(2))); const f2_t v = {lo, hi}; return __builtin_bit_cast(unsigned, __builtin_convertvector(v, b2_t)); }
; __device__ __forceinline__ float sigm(float x) { return __builtin_amdgcn_rcpf(1.0f + __builtin_amdgcn_exp2f(-1.4426950409f * x)); }
; __device__ __forceinline__ float gelu_tanh_f(float x) { return x * sigm(1.5957691216f * (x + 0.044715f * x * x * x)); }
;     template <int MODE> __device__ __forceinline__ void body(const f32x4 (&acc)[2][2][4][2], bf16_t* base, int ld, int row0, int cin, int rl0, int fq, const float* bp, float* sbase) const {
;     ...
;                     f32x4 v0 = acc[ai][bj][m][0] * rsv + bv[bj][0], v1 = acc[ai][bj][m][1] * rsv + bv[bj][1];
;                     if (MODE == 1 || MODE == 2) {
; #pragma unroll
;                         for (int e = 0; e < 4; ++e) { v0[e] = gelu_tanh_f(v0[e]); v1[e] = gelu_tanh_f(v1[e]); }
;                     } else if (MODE == 3) {
; #pragma unroll
;                         for (int e = 0; e < 4; ++e) { v0[e] = sigm(v0[e]); v1[e] = sigm(v1[e]); }
;                     }
;                     if (MODE == 2) {
; #pragma unroll
;                         for (int e = 0; e < 4; ++e) { s1 += v0[e] + v1[e]; s2 += v0[e] * v0[e] + v1[e] * v1[e]; }
;                     }
;                     u32x4 w; w.x = cvt_pk_bf16(v0[0], v0[1]); w.y = cvt_pk_bf16(v0[2], v0[3]); w.z = cvt_pk_bf16(v1[0], v1[1]); w.w = cvt_pk_bf16(v1[2], v1[3]);
;                     *(u32x4*)(rowp + bj * HALF) = w;
	v_mul_f32_e32 v160, 0xbfb8aa3b, v164
	v_exp_f32_e32 v160, v160
	v_mul_f32_e32 v163, 0xbfb8aa3b, v167
	v_exp_f32_e32 v153, v153
	v_exp_f32_e32 v157, v157
	v_add_f32_e32 v160, 1.0, v160
	v_rcp_f32_e32 v164, v160
	v_mul_f32_e32 v160, 0xbfb8aa3b, v161
	v_exp_f32_e32 v160, v160
	v_exp_f32_e32 v162, v162
	v_exp_f32_e32 v163, v163
	v_add_f32_e32 v153, 1.0, v153
	v_add_f32_e32 v160, 1.0, v160
	v_rcp_f32_e32 v161, v160
	v_mul_f32_e32 v160, 0xbfb8aa3b, v165
	v_exp_f32_e32 v160, v160
	v_add_f32_e32 v157, 1.0, v157
	v_add_f32_e32 v162, 1.0, v162
	v_add_f32_e32 v163, 1.0, v163
	v_add_f32_e32 v160, 1.0, v160
	v_rcp_f32_e32 v153, v153
	v_rcp_f32_e32 v157, v157
	v_rcp_f32_e32 v162, v162
	v_rcp_f32_e32 v163, v163
	v_rcp_f32_e32 v165, v160
	v_cvt_pk_bf16_f32 v161, v166, v161
	v_cvt_pk_bf16_f32 v160, v153, v162
	v_cvt_pk_bf16_f32 v162, v157, v163
	v_cvt_pk_bf16_f32 v163, v164, v165
	v_add_co_u32_e32 v164, vcc, s27, v154
	v_lshl_add_u64 v[158:159], v[154:155], 0, s[2:3]
	s_nop 0
	v_addc_co_u32_e32 v165, vcc, 0, v155, vcc
	global_store_dwordx4 v201, v[160:163], s[70:71] offset:2048
	v_pk_fma_f32 v[164:165], v[106:107], v[156:157], v[130:131] op_sel_hi:[1,0,1]
	s_mov_b64 s[2:3], 0x60000
	v_pk_fma_f32 v[160:161], v[110:111], v[156:157], v[134:135] op_sel_hi:[1,0,1]
	v_pk_fma_f32 v[162:163], v[108:109], v[156:157], v[132:133] op_sel_hi:[1,0,1]
	v_mul_f32_e32 v160, 0xbfb8aa3b, v160
	v_exp_f32_e32 v160, v160
	v_mul_f32_e32 v153, 0xbfb8aa3b, v162
	v_mul_f32_e32 v162, 0xbfb8aa3b, v163
	v_pk_fma_f32 v[156:157], v[104:105], v[156:157], v[128:129] op_sel_hi:[1,0,1]
	v_add_f32_e32 v160, 1.0, v160
	v_rcp_f32_e32 v163, v160
	v_mul_f32_e32 v160, 0xbfb8aa3b, v164
	v_exp_f32_e32 v160, v160
	v_mul_f32_e32 v156, 0xbfb8aa3b, v156
	v_mul_f32_e32 v157, 0xbfb8aa3b, v157
	v_exp_f32_e32 v153, v153
	v_add_f32_e32 v160, 1.0, v160
	v_rcp_f32_e32 v164, v160
	v_mul_f32_e32 v160, 0xbfb8aa3b, v161
	v_exp_f32_e32 v160, v160
	v_exp_f32_e32 v156, v156
	v_exp_f32_e32 v162, v162
	v_exp_f32_e32 v157, v157
	v_add_f32_e32 v160, 1.0, v160
	v_rcp_f32_e32 v161, v160
	v_mul_f32_e32 v160, 0xbfb8aa3b, v165
	v_exp_f32_e32 v160, v160
	v_add_f32_e32 v153, 1.0, v153
	v_add_f32_e32 v156, 1.0, v156
	v_add_f32_e32 v162, 1.0, v162
	v_add_f32_e32 v157, 1.0, v157
	v_add_f32_e32 v160, 1.0, v160
	v_rcp_f32_e32 v153, v153
	v_rcp_f32_e32 v156, v156
	v_rcp_f32_e32 v162, v162
	v_rcp_f32_e32 v157, v157
	v_rcp_f32_e32 v165, v160
	v_cvt_pk_bf16_f32 v161, v163, v161
	v_cvt_pk_bf16_f32 v160, v153, v162
	v_cvt_pk_bf16_f32 v162, v156, v157
	v_cvt_pk_bf16_f32 v163, v164, v165
	global_store_dwordx4 v201, v[160:163], s[70:71] offset:3072
	ds_read2_b32 v[158:159], v149 offset0:32 offset1:48
	v_lshl_add_u64 v[156:157], v[154:155], 0, s[18:19]
	s_waitcnt lgkmcnt(0)
	v_pk_fma_f32 v[160:161], v[86:87], v[158:159], v[142:143] op_sel_hi:[1,0,1]
	s_nop 0
	v_mul_f32_e32 v160, 0xbfb8aa3b, v160
	v_exp_f32_e32 v160, v160
	v_pk_fma_f32 v[162:163], v[84:85], v[158:159], v[140:141] op_sel_hi:[1,0,1]
	v_pk_fma_f32 v[164:165], v[82:83], v[158:159], v[138:139] op_sel_hi:[1,0,1]
	v_pk_fma_f32 v[166:167], v[80:81], v[158:159], v[136:137] op_sel_hi:[1,0,1]
	v_add_f32_e32 v160, 1.0, v160
	v_mul_f32_e32 v153, 0xbfb8aa3b, v162
	v_mul_f32_e32 v162, 0xbfb8aa3b, v166
	v_mul_f32_e32 v166, 0xbfb8aa3b, v167
	v_rcp_f32_e32 v167, v160
	v_mul_f32_e32 v160, 0xbfb8aa3b, v164
	v_exp_f32_e32 v160, v160
	v_mul_f32_e32 v163, 0xbfb8aa3b, v163
	v_exp_f32_e32 v153, v153
	v_exp_f32_e32 v163, v163
	v_add_f32_e32 v160, 1.0, v160
	v_rcp_f32_e32 v164, v160
	v_mul_f32_e32 v160, 0xbfb8aa3b, v161
	v_exp_f32_e32 v160, v160
	v_exp_f32_e32 v162, v162
	v_exp_f32_e32 v166, v166
	v_add_f32_e32 v153, 1.0, v153
	v_add_f32_e32 v160, 1.0, v160
	v_rcp_f32_e32 v161, v160
	v_mul_f32_e32 v160, 0xbfb8aa3b, v165
	v_exp_f32_e32 v160, v160
	v_add_f32_e32 v163, 1.0, v163
	v_rcp_f32_e32 v153, v153
	v_add_f32_e32 v162, 1.0, v162
	v_add_f32_e32 v160, 1.0, v160
	v_rcp_f32_e32 v163, v163
	v_add_f32_e32 v166, 1.0, v166
	v_rcp_f32_e32 v165, v160
	v_rcp_f32_e32 v162, v162
	v_rcp_f32_e32 v166, v166
	v_cvt_pk_bf16_f32 v160, v153, v163
	v_cvt_pk_bf16_f32 v163, v164, v165
	v_add_co_u32_e32 v164, vcc, s13, v154
	v_cvt_pk_bf16_f32 v161, v167, v161
	v_cvt_pk_bf16_f32 v162, v162, v166
	v_addc_co_u32_e32 v165, vcc, 0, v155, vcc
	global_store_dwordx4 v202, v[160:163], s[70:71]
	v_pk_fma_f32 v[164:165], v[90:91], v[158:159], v[130:131] op_sel_hi:[1,0,1]
	v_pk_fma_f32 v[166:167], v[88:89], v[158:159], v[128:129] op_sel_hi:[1,0,1]
	v_pk_fma_f32 v[160:161], v[94:95], v[158:159], v[134:135] op_sel_hi:[1,0,1]
	v_pk_fma_f32 v[162:163], v[92:93], v[158:159], v[132:133] op_sel_hi:[1,0,1]
	v_mul_f32_e32 v160, 0xbfb8aa3b, v160
	v_exp_f32_e32 v160, v160
	v_mul_f32_e32 v158, 0xbfb8aa3b, v166
	v_mul_f32_e32 v153, 0xbfb8aa3b, v162
	v_mul_f32_e32 v162, 0xbfb8aa3b, v163
	v_add_f32_e32 v160, 1.0, v160
	v_rcp_f32_e32 v166, v160
	v_mul_f32_e32 v160, 0xbfb8aa3b, v164
	v_exp_f32_e32 v160, v160
	v_mul_f32_e32 v163, 0xbfb8aa3b, v167
	v_exp_f32_e32 v153, v153
	v_exp_f32_e32 v158, v158
	v_add_f32_e32 v160, 1.0, v160
	v_rcp_f32_e32 v164, v160
	v_mul_f32_e32 v160, 0xbfb8aa3b, v161
	v_exp_f32_e32 v160, v160
	v_exp_f32_e32 v162, v162
	v_exp_f32_e32 v163, v163
	v_add_f32_e32 v153, 1.0, v153
	v_add_f32_e32 v160, 1.0, v160
	v_rcp_f32_e32 v161, v160
	v_mul_f32_e32 v160, 0xbfb8aa3b, v165
	v_exp_f32_e32 v160, v160
	v_add_f32_e32 v158, 1.0, v158
	v_add_f32_e32 v162, 1.0, v162
	v_add_f32_e32 v163, 1.0, v163
	v_add_f32_e32 v160, 1.0, v160
	v_rcp_f32_e32 v153, v153
	v_rcp_f32_e32 v158, v158
	v_rcp_f32_e32 v162, v162
	v_rcp_f32_e32 v163, v163
	v_rcp_f32_e32 v165, v160
	v_cvt_pk_bf16_f32 v161, v166, v161
	v_cvt_pk_bf16_f32 v160, v153, v162
; __device__ __forceinline__ unsigned cvt_pk_bf16(float lo, float hi) { typedef float f2_t __attribute__((ext_vector_type(2))); typedef __bf16 b2_t __attribute__((ext_vector_type(2))); const f2_t v = {lo, hi}; return __builtin_bit_cast(unsigned, __builtin_convertvector(v, b2_t)); }
; __device__ __forceinline__ float sigm(float x) { return __builtin_amdgcn_rcpf(1.0f + __builtin_amdgcn_exp2f(-1.4426950409f * x)); }
; __device__ __forceinline__ float gelu_tanh_f(float x) { return x * sigm(1.5957691216f * (x + 0.044715f * x * x * x)); }
;     template <int MODE> __device__ __forceinline__ void body(const f32x4 (&acc)[2][2][4][2], bf16_t* base, int ld, int row0, int cin, int rl0, int fq, const float* bp, float* sbase) const {
;     ...
;                     f32x4 v0 = acc[ai][bj][m][0] * rsv + bv[bj][0], v1 = acc[ai][bj][m][1] * rsv + bv[bj][1];
;                     if (MODE == 1 || MODE == 2) {
; #pragma unroll
;                         for (int e = 0; e < 4; ++e) { v0[e] = gelu_tanh_f(v0[e]); v1[e] = gelu_tanh_f(v1[e]); }
;                     } else if (MODE == 3) {
; #pragma unroll
;                         for (int e = 0; e < 4; ++e) { v0[e] = sigm(v0[e]); v1[e] = sigm(v1[e]); }
;                     }
;                     if (MODE == 2) {
; #pragma unroll
;                         for (int e = 0; e < 4; ++e) { s1 += v0[e] + v1[e]; s2 += v0[e] * v0[e] + v1[e] * v1[e]; }
;                     }
;                     u32x4 w; w.x = cvt_pk_bf16(v0[0], v0[1]); w.y = cvt_pk_bf16(v0[2], v0[3]); w.z = cvt_pk_bf16(v1[0], v1[1]); w.w = cvt_pk_bf16(v1[2], v1[3]);
;                     *(u32x4*)(rowp + bj * HALF) = w;
	v_cvt_pk_bf16_f32 v162, v158, v163
	v_cvt_pk_bf16_f32 v163, v164, v165
	global_store_dwordx4 v202, v[160:163], s[70:71] offset:1024
	v_lshl_add_u64 v[156:157], v[154:155], 0, s[2:3]
	s_mov_b64 s[2:3], 0x100000
	v_mov_b32_e32 v162, v159
	v_pk_fma_f32 v[158:159], v[46:47], v[162:163], v[142:143] op_sel_hi:[1,0,1]
	v_pk_fma_f32 v[160:161], v[44:45], v[162:163], v[140:141] op_sel_hi:[1,0,1]
	v_mul_f32_e32 v158, 0xbfb8aa3b, v158
	v_exp_f32_e32 v158, v158
	v_pk_fma_f32 v[164:165], v[42:43], v[162:163], v[138:139] op_sel_hi:[1,0,1]
	v_pk_fma_f32 v[166:167], v[40:41], v[162:163], v[136:137] op_sel_hi:[1,0,1]
	v_mul_f32_e32 v153, 0xbfb8aa3b, v160
	v_add_f32_e32 v158, 1.0, v158
	v_mul_f32_e32 v160, 0xbfb8aa3b, v166
	v_rcp_f32_e32 v166, v158
	v_mul_f32_e32 v158, 0xbfb8aa3b, v164
	v_exp_f32_e32 v158, v158
	v_mul_f32_e32 v161, 0xbfb8aa3b, v161
	v_exp_f32_e32 v153, v153
	v_exp_f32_e32 v161, v161
	v_add_f32_e32 v158, 1.0, v158
	v_rcp_f32_e32 v164, v158
	v_mul_f32_e32 v158, 0xbfb8aa3b, v159
	v_exp_f32_e32 v158, v158
	v_mul_f32_e32 v163, 0xbfb8aa3b, v167
	v_exp_f32_e32 v160, v160
	v_exp_f32_e32 v163, v163
	v_add_f32_e32 v158, 1.0, v158
	v_rcp_f32_e32 v159, v158
	v_mul_f32_e32 v158, 0xbfb8aa3b, v165
	v_exp_f32_e32 v158, v158
	v_add_f32_e32 v153, 1.0, v153
	v_add_f32_e32 v161, 1.0, v161
	v_rcp_f32_e32 v153, v153
	v_add_f32_e32 v158, 1.0, v158
	v_add_f32_e32 v160, 1.0, v160
	v_rcp_f32_e32 v161, v161
	v_add_f32_e32 v163, 1.0, v163
	v_rcp_f32_e32 v165, v158
	v_rcp_f32_e32 v160, v160
	v_rcp_f32_e32 v163, v163
	v_cvt_pk_bf16_f32 v158, v153, v161
	v_cvt_pk_bf16_f32 v161, v164, v165
	v_add_co_u32_e32 v164, vcc, s1, v154
	v_cvt_pk_bf16_f32 v159, v166, v159
	v_cvt_pk_bf16_f32 v160, v160, v163
	v_addc_co_u32_e32 v165, vcc, 0, v155, vcc
	global_store_dwordx4 v202, v[158:161], s[70:71] offset:2048
	v_pk_fma_f32 v[164:165], v[50:51], v[162:163], v[130:131] op_sel_hi:[1,0,1]
	s_mov_b32 s1, 0x100000
	v_pk_fma_f32 v[158:159], v[54:55], v[162:163], v[134:135] op_sel_hi:[1,0,1]
	v_pk_fma_f32 v[160:161], v[52:53], v[162:163], v[132:133] op_sel_hi:[1,0,1]
	v_mul_f32_e32 v158, 0xbfb8aa3b, v158
	v_exp_f32_e32 v158, v158
	v_pk_fma_f32 v[162:163], v[48:49], v[162:163], v[128:129] op_sel_hi:[1,0,1]
	v_mul_f32_e32 v153, 0xbfb8aa3b, v160
	v_mul_f32_e32 v160, 0xbfb8aa3b, v162
	v_add_f32_e32 v158, 1.0, v158
	v_mul_f32_e32 v162, 0xbfb8aa3b, v163
	v_rcp_f32_e32 v163, v158
	v_mul_f32_e32 v158, 0xbfb8aa3b, v164
	v_exp_f32_e32 v158, v158
	v_exp_f32_e32 v160, v160
	v_exp_f32_e32 v162, v162
	v_mul_f32_e32 v161, 0xbfb8aa3b, v161
	v_add_f32_e32 v158, 1.0, v158
	v_rcp_f32_e32 v164, v158
	v_mul_f32_e32 v158, 0xbfb8aa3b, v159
	v_exp_f32_e32 v158, v158
	v_exp_f32_e32 v153, v153
	v_add_f32_e32 v160, 1.0, v160
	v_exp_f32_e32 v161, v161
	v_add_f32_e32 v158, 1.0, v158
	v_rcp_f32_e32 v159, v158
	v_mul_f32_e32 v158, 0xbfb8aa3b, v165
	v_add_f32_e32 v162, 1.0, v162
	v_exp_f32_e32 v158, v158
	v_rcp_f32_e32 v160, v160
	v_rcp_f32_e32 v162, v162
	v_add_f32_e32 v153, 1.0, v153
	v_add_f32_e32 v161, 1.0, v161
	v_add_f32_e32 v158, 1.0, v158
	v_rcp_f32_e32 v153, v153
	v_rcp_f32_e32 v161, v161
	v_rcp_f32_e32 v165, v158
	v_cvt_pk_bf16_f32 v160, v160, v162
	ds_read_b32 v162, v151
	v_cvt_pk_bf16_f32 v158, v153, v161
	v_cvt_pk_bf16_f32 v159, v163, v159
	v_cvt_pk_bf16_f32 v161, v164, v165
	global_store_dwordx4 v202, v[158:161], s[70:71] offset:3072
	s_waitcnt lgkmcnt(0)
	v_pk_fma_f32 v[156:157], v[66:67], v[162:163], v[142:143] op_sel_hi:[1,0,1]
	v_pk_fma_f32 v[164:165], v[70:71], v[162:163], v[138:139] op_sel_hi:[1,0,1]
	v_mul_f32_e32 v156, 0xbfb8aa3b, v156
	v_exp_f32_e32 v156, v156
	v_pk_fma_f32 v[158:159], v[64:65], v[162:163], v[140:141] op_sel_hi:[1,0,1]
	v_pk_fma_f32 v[166:167], v[68:69], v[162:163], v[136:137] op_sel_hi:[1,0,1]
	v_mul_f32_e32 v151, 0xbfb8aa3b, v158
	v_add_f32_e32 v156, 1.0, v156
	v_rcp_f32_e32 v163, v156
	v_mul_f32_e32 v156, 0xbfb8aa3b, v164
	v_exp_f32_e32 v156, v156
	v_mul_f32_e32 v153, 0xbfb8aa3b, v166
	v_mul_f32_e32 v158, 0xbfb8aa3b, v159
	v_mul_f32_e32 v159, 0xbfb8aa3b, v167
	v_add_f32_e32 v156, 1.0, v156
	v_rcp_f32_e32 v164, v156
	v_mul_f32_e32 v156, 0xbfb8aa3b, v157
	v_exp_f32_e32 v156, v156
	v_exp_f32_e32 v151, v151
	v_exp_f32_e32 v153, v153
	v_exp_f32_e32 v158, v158
	v_add_f32_e32 v156, 1.0, v156
	v_rcp_f32_e32 v157, v156
	v_mul_f32_e32 v156, 0xbfb8aa3b, v165
	v_exp_f32_e32 v159, v159
	v_exp_f32_e32 v156, v156
	v_add_f32_e32 v151, 1.0, v151
	v_add_f32_e32 v153, 1.0, v153
	v_add_f32_e32 v158, 1.0, v158
	v_add_f32_e32 v159, 1.0, v159
	v_add_f32_e32 v156, 1.0, v156
	v_rcp_f32_e32 v151, v151
	v_rcp_f32_e32 v153, v153
	v_rcp_f32_e32 v158, v158
	v_rcp_f32_e32 v159, v159
	v_rcp_f32_e32 v165, v156
	v_cvt_pk_bf16_f32 v157, v163, v157
	v_cvt_pk_bf16_f32 v156, v151, v158
	v_cvt_pk_bf16_f32 v158, v153, v159
	v_cvt_pk_bf16_f32 v159, v164, v165
	v_add_co_u32_e32 v164, vcc, s1, v154
	v_lshl_add_u64 v[160:161], v[154:155], 0, s[2:3]
	s_nop 0
	v_addc_co_u32_e32 v165, vcc, 0, v155, vcc
	global_store_dwordx4 v203, v[156:159], s[70:71]
	v_pk_fma_f32 v[164:165], v[78:79], v[162:163], v[130:131] op_sel_hi:[1,0,1]
	s_mov_b32 s1, 0x120000
	v_pk_fma_f32 v[156:157], v[74:75], v[162:163], v[134:135] op_sel_hi:[1,0,1]
	v_pk_fma_f32 v[158:159], v[72:73], v[162:163], v[132:133] op_sel_hi:[1,0,1]
	v_mul_f32_e32 v156, 0xbfb8aa3b, v156
	v_exp_f32_e32 v156, v156
	v_pk_fma_f32 v[162:163], v[76:77], v[162:163], v[128:129] op_sel_hi:[1,0,1]
	v_mul_f32_e32 v151, 0xbfb8aa3b, v158
	v_mul_f32_e32 v153, 0xbfb8aa3b, v162
	v_add_f32_e32 v156, 1.0, v156
	v_rcp_f32_e32 v162, v156
	v_mul_f32_e32 v156, 0xbfb8aa3b, v164
	v_exp_f32_e32 v156, v156
	v_mul_f32_e32 v158, 0xbfb8aa3b, v159
	v_mul_f32_e32 v159, 0xbfb8aa3b, v163
	v_exp_f32_e32 v151, v151
	v_add_f32_e32 v156, 1.0, v156
	v_rcp_f32_e32 v163, v156
	v_mul_f32_e32 v156, 0xbfb8aa3b, v157
	v_exp_f32_e32 v156, v156
	v_exp_f32_e32 v153, v153
	v_exp_f32_e32 v158, v158
	v_exp_f32_e32 v159, v159
	v_add_f32_e32 v156, 1.0, v156
	v_rcp_f32_e32 v157, v156
	v_mul_f32_e32 v156, 0xbfb8aa3b, v165
	v_exp_f32_e32 v156, v156
	v_add_f32_e32 v151, 1.0, v151
	v_add_f32_e32 v153, 1.0, v153
	v_add_f32_e32 v158, 1.0, v158
	v_add_f32_e32 v159, 1.0, v159
	v_add_f32_e32 v156, 1.0, v156
	v_rcp_f32_e32 v151, v151
	v_rcp_f32_e32 v153, v153
	v_rcp_f32_e32 v158, v158
	v_rcp_f32_e32 v159, v159
	v_rcp_f32_e32 v164, v156
	v_cvt_pk_bf16_f32 v157, v162, v157
	v_cvt_pk_bf16_f32 v156, v151, v158
	v_cvt_pk_bf16_f32 v158, v153, v159
	v_cvt_pk_bf16_f32 v159, v163, v164
	ds_read2_b32 v[162:163], v149 offset0:144 offset1:160
	global_store_dwordx4 v203, v[156:159], s[70:71] offset:1024
	s_mov_b64 s[2:3], 0x120000
	v_lshl_add_u64 v[160:161], v[154:155], 0, s[2:3]
	s_mov_b64 s[2:3], 0x140000
	s_waitcnt lgkmcnt(0)
; __device__ __forceinline__ unsigned cvt_pk_bf16(float lo, float hi) { typedef float f2_t __attribute__((ext_vector_type(2))); typedef __bf16 b2_t __attribute__((ext_vector_type(2))); const f2_t v = {lo, hi}; return __builtin_bit_cast(unsigned, __builtin_convertvector(v, b2_t)); }
; __device__ __forceinline__ float sigm(float x) { return __builtin_amdgcn_rcpf(1.0f + __builtin_amdgcn_exp2f(-1.4426950409f * x)); }
; __device__ __forceinline__ float gelu_tanh_f(float x) { return x * sigm(1.5957691216f * (x + 0.044715f * x * x * x)); }
;     template <int MODE> __device__ __forceinline__ void body(const f32x4 (&acc)[2][2][4][2], bf16_t* base, int ld, int row0, int cin, int rl0, int fq, const float* bp, float* sbase) const {
;     ...
;                     f32x4 v0 = acc[ai][bj][m][0] * rsv + bv[bj][0], v1 = acc[ai][bj][m][1] * rsv + bv[bj][1];
;                     if (MODE == 1 || MODE == 2) {
; #pragma unroll
;                         for (int e = 0; e < 4; ++e) { v0[e] = gelu_tanh_f(v0[e]); v1[e] = gelu_tanh_f(v1[e]); }
;                     } else if (MODE == 3) {
; #pragma unroll
;                         for (int e = 0; e < 4; ++e) { v0[e] = sigm(v0[e]); v1[e] = sigm(v1[e]); }
;                     }
;                     if (MODE == 2) {
; #pragma unroll
;                         for (int e = 0; e < 4; ++e) { s1 += v0[e] + v1[e]; s2 += v0[e] * v0[e] + v1[e] * v1[e]; }
;                     }
;                     u32x4 w; w.x = cvt_pk_bf16(v0[0], v0[1]); w.y = cvt_pk_bf16(v0[2], v0[3]); w.z = cvt_pk_bf16(v1[0], v1[1]); w.w = cvt_pk_bf16(v1[2], v1[3]);
;                     *(u32x4*)(rowp + bj * HALF) = w;
	v_pk_fma_f32 v[156:157], v[34:35], v[162:163], v[142:143] op_sel_hi:[1,0,1]
	v_pk_fma_f32 v[164:165], v[38:39], v[162:163], v[138:139] op_sel_hi:[1,0,1]
	v_mul_f32_e32 v156, 0xbfb8aa3b, v156
	v_exp_f32_e32 v156, v156
	v_pk_fma_f32 v[166:167], v[36:37], v[162:163], v[136:137] op_sel_hi:[1,0,1]
	v_pk_fma_f32 v[158:159], v[32:33], v[162:163], v[140:141] op_sel_hi:[1,0,1]
	v_mul_f32_e32 v153, 0xbfb8aa3b, v166
	v_add_f32_e32 v156, 1.0, v156
	v_rcp_f32_e32 v166, v156
	v_mul_f32_e32 v156, 0xbfb8aa3b, v164
	v_exp_f32_e32 v156, v156
	v_mul_f32_e32 v151, 0xbfb8aa3b, v158
	v_mul_f32_e32 v158, 0xbfb8aa3b, v159
	v_mul_f32_e32 v159, 0xbfb8aa3b, v167
	v_add_f32_e32 v156, 1.0, v156
	v_rcp_f32_e32 v164, v156
	v_mul_f32_e32 v156, 0xbfb8aa3b, v157
	v_exp_f32_e32 v156, v156
	v_exp_f32_e32 v151, v151
	v_exp_f32_e32 v153, v153
	v_exp_f32_e32 v158, v158
	v_add_f32_e32 v156, 1.0, v156
	v_rcp_f32_e32 v157, v156
	v_mul_f32_e32 v156, 0xbfb8aa3b, v165
	v_exp_f32_e32 v159, v159
	v_exp_f32_e32 v156, v156
	v_add_f32_e32 v151, 1.0, v151
	v_add_f32_e32 v153, 1.0, v153
	v_add_f32_e32 v158, 1.0, v158
	v_add_f32_e32 v159, 1.0, v159
	v_add_f32_e32 v156, 1.0, v156
	v_rcp_f32_e32 v151, v151
	v_rcp_f32_e32 v153, v153
	v_rcp_f32_e32 v158, v158
	v_rcp_f32_e32 v159, v159
	v_rcp_f32_e32 v165, v156
	v_cvt_pk_bf16_f32 v157, v166, v157
	v_cvt_pk_bf16_f32 v156, v151, v158
	v_cvt_pk_bf16_f32 v158, v153, v159
	v_cvt_pk_bf16_f32 v159, v164, v165
	v_add_co_u32_e32 v164, vcc, s1, v154
	v_pk_fma_f32 v[166:167], v[60:61], v[162:163], v[128:129] op_sel_hi:[1,0,1]
	s_nop 0
	v_addc_co_u32_e32 v165, vcc, 0, v155, vcc
	global_store_dwordx4 v203, v[156:159], s[70:71] offset:2048
	v_pk_fma_f32 v[164:165], v[62:63], v[162:163], v[130:131] op_sel_hi:[1,0,1]
	v_mul_f32_e32 v153, 0xbfb8aa3b, v166
	v_pk_fma_f32 v[156:157], v[58:59], v[162:163], v[134:135] op_sel_hi:[1,0,1]
	v_pk_fma_f32 v[158:159], v[56:57], v[162:163], v[132:133] op_sel_hi:[1,0,1]
	v_mul_f32_e32 v156, 0xbfb8aa3b, v156
	v_exp_f32_e32 v156, v156
	v_mul_f32_e32 v151, 0xbfb8aa3b, v158
	v_mul_f32_e32 v158, 0xbfb8aa3b, v159
	v_mul_f32_e32 v159, 0xbfb8aa3b, v167
	v_add_f32_e32 v156, 1.0, v156
	v_rcp_f32_e32 v162, v156
	v_mul_f32_e32 v156, 0xbfb8aa3b, v164
	v_exp_f32_e32 v156, v156
	v_exp_f32_e32 v151, v151
	v_exp_f32_e32 v153, v153
	v_exp_f32_e32 v158, v158
	v_add_f32_e32 v156, 1.0, v156
	v_rcp_f32_e32 v164, v156
	v_mul_f32_e32 v156, 0xbfb8aa3b, v157
	v_exp_f32_e32 v156, v156
	v_exp_f32_e32 v159, v159
	v_add_f32_e32 v151, 1.0, v151
	v_add_f32_e32 v153, 1.0, v153
	v_add_f32_e32 v156, 1.0, v156
	v_rcp_f32_e32 v157, v156
	v_mul_f32_e32 v156, 0xbfb8aa3b, v165
	v_exp_f32_e32 v156, v156
	v_add_f32_e32 v158, 1.0, v158
	v_add_f32_e32 v159, 1.0, v159
	v_rcp_f32_e32 v151, v151
	v_add_f32_e32 v156, 1.0, v156
	v_rcp_f32_e32 v153, v153
	v_rcp_f32_e32 v158, v158
	v_rcp_f32_e32 v159, v159
	v_rcp_f32_e32 v165, v156
	v_cvt_pk_bf16_f32 v157, v162, v157
	v_cvt_pk_bf16_f32 v156, v151, v158
	v_cvt_pk_bf16_f32 v158, v153, v159
	v_cvt_pk_bf16_f32 v159, v164, v165
	v_mov_b32_e32 v162, v163
	global_store_dwordx4 v203, v[156:159], s[70:71] offset:3072
	v_pk_fma_f32 v[164:165], v[22:23], v[162:163], v[138:139] op_sel_hi:[1,0,1]
	v_pk_fma_f32 v[166:167], v[20:21], v[162:163], v[136:137] op_sel_hi:[1,0,1]
	v_pk_fma_f32 v[156:157], v[18:19], v[162:163], v[142:143] op_sel_hi:[1,0,1]
	v_pk_fma_f32 v[158:159], v[16:17], v[162:163], v[140:141] op_sel_hi:[1,0,1]
	v_mul_f32_e32 v156, 0xbfb8aa3b, v156
	v_exp_f32_e32 v156, v156
	v_mul_f32_e32 v151, 0xbfb8aa3b, v158
	v_mul_f32_e32 v153, 0xbfb8aa3b, v166
	v_mul_f32_e32 v158, 0xbfb8aa3b, v159
	v_add_f32_e32 v156, 1.0, v156
	v_rcp_f32_e32 v163, v156
	v_mul_f32_e32 v156, 0xbfb8aa3b, v164
	v_exp_f32_e32 v156, v156
	v_mul_f32_e32 v159, 0xbfb8aa3b, v167
	v_exp_f32_e32 v151, v151
	v_exp_f32_e32 v153, v153
	v_add_f32_e32 v156, 1.0, v156
	v_rcp_f32_e32 v164, v156
	v_mul_f32_e32 v156, 0xbfb8aa3b, v157
	v_exp_f32_e32 v156, v156
	v_exp_f32_e32 v158, v158
	v_exp_f32_e32 v159, v159
	v_add_f32_e32 v151, 1.0, v151
	v_add_f32_e32 v156, 1.0, v156
	v_rcp_f32_e32 v157, v156
	v_mul_f32_e32 v156, 0xbfb8aa3b, v165
	v_exp_f32_e32 v156, v156
	v_add_f32_e32 v153, 1.0, v153
	v_add_f32_e32 v158, 1.0, v158
	v_add_f32_e32 v159, 1.0, v159
	v_add_f32_e32 v156, 1.0, v156
	v_rcp_f32_e32 v151, v151
	v_rcp_f32_e32 v153, v153
	v_rcp_f32_e32 v158, v158
	v_rcp_f32_e32 v159, v159
	v_rcp_f32_e32 v165, v156
	s_mov_b32 s1, 0x140000
	v_cvt_pk_bf16_f32 v156, v151, v158
	v_cvt_pk_bf16_f32 v158, v153, v159
	v_cvt_pk_bf16_f32 v159, v164, v165
	v_add_co_u32_e32 v164, vcc, s1, v154
	v_cvt_pk_bf16_f32 v157, v163, v157
	s_nop 0
	v_addc_co_u32_e32 v165, vcc, 0, v155, vcc
	global_store_dwordx4 v204, v[156:159], s[70:71]
	v_pk_fma_f32 v[164:165], v[30:31], v[162:163], v[130:131] op_sel_hi:[1,0,1]
	v_lshl_add_u64 v[160:161], v[154:155], 0, s[2:3]
	v_pk_fma_f32 v[156:157], v[26:27], v[162:163], v[134:135] op_sel_hi:[1,0,1]
	v_pk_fma_f32 v[158:159], v[24:25], v[162:163], v[132:133] op_sel_hi:[1,0,1]
	v_mul_f32_e32 v156, 0xbfb8aa3b, v156
	v_exp_f32_e32 v156, v156
	v_pk_fma_f32 v[162:163], v[28:29], v[162:163], v[128:129] op_sel_hi:[1,0,1]
	v_mul_f32_e32 v151, 0xbfb8aa3b, v158
	v_mul_f32_e32 v153, 0xbfb8aa3b, v162
	v_add_f32_e32 v156, 1.0, v156
	v_rcp_f32_e32 v162, v156
	v_mul_f32_e32 v156, 0xbfb8aa3b, v164
	v_exp_f32_e32 v156, v156
	v_mul_f32_e32 v158, 0xbfb8aa3b, v159
	v_mul_f32_e32 v159, 0xbfb8aa3b, v163
	v_exp_f32_e32 v151, v151
	v_add_f32_e32 v156, 1.0, v156
	v_rcp_f32_e32 v163, v156
	v_mul_f32_e32 v156, 0xbfb8aa3b, v157
	v_exp_f32_e32 v156, v156
	v_exp_f32_e32 v153, v153
	v_exp_f32_e32 v158, v158
	v_exp_f32_e32 v159, v159
	v_add_f32_e32 v156, 1.0, v156
	v_rcp_f32_e32 v157, v156
	v_mul_f32_e32 v156, 0xbfb8aa3b, v165
	v_exp_f32_e32 v156, v156
	v_add_f32_e32 v151, 1.0, v151
	v_add_f32_e32 v153, 1.0, v153
	v_add_f32_e32 v158, 1.0, v158
	v_add_f32_e32 v159, 1.0, v159
	v_add_f32_e32 v156, 1.0, v156
	v_rcp_f32_e32 v151, v151
	v_rcp_f32_e32 v153, v153
	v_rcp_f32_e32 v158, v158
	v_rcp_f32_e32 v159, v159
	v_rcp_f32_e32 v164, v156
	v_cvt_pk_bf16_f32 v157, v162, v157
	v_cvt_pk_bf16_f32 v156, v151, v158
	v_cvt_pk_bf16_f32 v158, v153, v159
	v_cvt_pk_bf16_f32 v159, v163, v164
	global_store_dwordx4 v204, v[156:159], s[70:71] offset:1024
	ds_read_b32 v158, v149 offset:704
	s_mov_b32 s1, 0x160000
	s_mov_b64 s[2:3], 0x160000
	v_lshl_add_u64 v[156:157], v[154:155], 0, s[2:3]
	s_waitcnt lgkmcnt(0)
; __device__ __forceinline__ unsigned cvt_pk_bf16(float lo, float hi) { typedef float f2_t __attribute__((ext_vector_type(2))); typedef __bf16 b2_t __attribute__((ext_vector_type(2))); const f2_t v = {lo, hi}; return __builtin_bit_cast(unsigned, __builtin_convertvector(v, b2_t)); }
; __device__ __forceinline__ float sigm(float x) { return __builtin_amdgcn_rcpf(1.0f + __builtin_amdgcn_exp2f(-1.4426950409f * x)); }
; __device__ __forceinline__ float gelu_tanh_f(float x) { return x * sigm(1.5957691216f * (x + 0.044715f * x * x * x)); }
;     template <int MODE> __device__ __forceinline__ void body(const f32x4 (&acc)[2][2][4][2], bf16_t* base, int ld, int row0, int cin, int rl0, int fq, const float* bp, float* sbase) const {
;     ...
;                     f32x4 v0 = acc[ai][bj][m][0] * rsv + bv[bj][0], v1 = acc[ai][bj][m][1] * rsv + bv[bj][1];
;                     if (MODE == 1 || MODE == 2) {
; #pragma unroll
;                         for (int e = 0; e < 4; ++e) { v0[e] = gelu_tanh_f(v0[e]); v1[e] = gelu_tanh_f(v1[e]); }
;                     } else if (MODE == 3) {
; #pragma unroll
;                         for (int e = 0; e < 4; ++e) { v0[e] = sigm(v0[e]); v1[e] = sigm(v1[e]); }
;                     }
;                     if (MODE == 2) {
; #pragma unroll
;                         for (int e = 0; e < 4; ++e) { s1 += v0[e] + v1[e]; s2 += v0[e] * v0[e] + v1[e] * v1[e]; }
;                     }
;                     u32x4 w; w.x = cvt_pk_bf16(v0[0], v0[1]); w.y = cvt_pk_bf16(v0[2], v0[3]); w.z = cvt_pk_bf16(v1[0], v1[1]); w.w = cvt_pk_bf16(v1[2], v1[3]);
;                     *(u32x4*)(rowp + bj * HALF) = w;
	v_pk_fma_f32 v[136:137], v[0:1], v[158:159], v[136:137] op_sel_hi:[1,0,1]
	v_pk_fma_f32 v[138:139], v[2:3], v[158:159], v[138:139] op_sel_hi:[1,0,1]
	v_mul_f32_e32 v136, 0xbfb8aa3b, v136
	v_exp_f32_e32 v136, v136
	v_mul_f32_e32 v137, 0xbfb8aa3b, v137
	v_mul_f32_e32 v138, 0xbfb8aa3b, v138
	v_exp_f32_e32 v137, v137
	v_exp_f32_e32 v138, v138
	v_pk_fma_f32 v[140:141], v[4:5], v[158:159], v[140:141] op_sel_hi:[1,0,1]
	v_add_f32_e32 v136, 1.0, v136
	v_pk_fma_f32 v[142:143], v[6:7], v[158:159], v[142:143] op_sel_hi:[1,0,1]
	v_mul_f32_e32 v140, 0xbfb8aa3b, v140
	v_rcp_f32_e32 v149, v136
	v_mul_f32_e32 v136, 0xbfb8aa3b, v141
	v_add_f32_e32 v137, 1.0, v137
	v_add_f32_e32 v138, 1.0, v138
	v_exp_f32_e32 v140, v140
	v_exp_f32_e32 v136, v136
	v_rcp_f32_e32 v141, v137
	v_mul_f32_e32 v137, 0xbfb8aa3b, v142
	v_rcp_f32_e32 v142, v138
	v_mul_f32_e32 v138, 0xbfb8aa3b, v143
	v_mul_f32_e32 v139, 0xbfb8aa3b, v139
	v_exp_f32_e32 v137, v137
	v_exp_f32_e32 v138, v138
	v_exp_f32_e32 v139, v139
	v_add_f32_e32 v140, 1.0, v140
	v_add_f32_e32 v136, 1.0, v136
	v_pk_fma_f32 v[130:131], v[10:11], v[158:159], v[130:131] op_sel_hi:[1,0,1]
	v_pk_fma_f32 v[128:129], v[8:9], v[158:159], v[128:129] op_sel_hi:[1,0,1]
	v_rcp_f32_e32 v140, v140
	v_rcp_f32_e32 v136, v136
	v_add_f32_e32 v137, 1.0, v137
	v_add_f32_e32 v138, 1.0, v138
	v_add_f32_e32 v139, 1.0, v139
	v_mul_f32_e32 v128, 0xbfb8aa3b, v128
	v_mul_f32_e32 v129, 0xbfb8aa3b, v129
	v_mul_f32_e32 v130, 0xbfb8aa3b, v130
	v_rcp_f32_e32 v137, v137
	v_rcp_f32_e32 v138, v138
	v_rcp_f32_e32 v139, v139
	v_exp_f32_e32 v128, v128
	v_exp_f32_e32 v129, v129
	v_exp_f32_e32 v130, v130
	v_cvt_pk_bf16_f32 v136, v140, v136
	v_add_co_u32_e32 v140, vcc, s1, v154
	v_cvt_pk_bf16_f32 v137, v137, v138
	v_cvt_pk_bf16_f32 v138, v149, v141
	v_cvt_pk_bf16_f32 v139, v142, v139
	v_addc_co_u32_e32 v141, vcc, 0, v155, vcc
	v_pk_fma_f32 v[134:135], v[14:15], v[158:159], v[134:135] op_sel_hi:[1,0,1]
	v_pk_fma_f32 v[132:133], v[12:13], v[158:159], v[132:133] op_sel_hi:[1,0,1]
	v_add_f32_e32 v128, 1.0, v128
	v_add_f32_e32 v129, 1.0, v129
	v_add_f32_e32 v130, 1.0, v130
	global_store_dwordx4 v204, v[136:139], s[70:71] offset:2048
	v_mul_f32_e32 v132, 0xbfb8aa3b, v132
	v_mul_f32_e32 v131, 0xbfb8aa3b, v131
	v_rcp_f32_e32 v136, v128
	v_mul_f32_e32 v128, 0xbfb8aa3b, v133
	v_rcp_f32_e32 v133, v129
	v_mul_f32_e32 v129, 0xbfb8aa3b, v134
	v_rcp_f32_e32 v134, v130
	v_mul_f32_e32 v130, 0xbfb8aa3b, v135
	v_exp_f32_e32 v132, v132
	v_exp_f32_e32 v128, v128
	v_exp_f32_e32 v129, v129
	v_exp_f32_e32 v130, v130
	v_exp_f32_e32 v131, v131
	v_add_f32_e32 v132, 1.0, v132
	v_add_f32_e32 v128, 1.0, v128
	v_add_f32_e32 v129, 1.0, v129
	v_add_f32_e32 v130, 1.0, v130
	v_add_f32_e32 v131, 1.0, v131
	v_rcp_f32_e32 v132, v132
	v_rcp_f32_e32 v128, v128
	v_rcp_f32_e32 v129, v129
	v_rcp_f32_e32 v130, v130
	v_rcp_f32_e32 v131, v131
	v_cvt_pk_bf16_f32 v128, v132, v128
	v_cvt_pk_bf16_f32 v129, v129, v130
	v_cvt_pk_bf16_f32 v130, v136, v133
	v_cvt_pk_bf16_f32 v131, v134, v131
	global_store_dwordx4 v204, v[128:131], s[70:71] offset:3072

;     __device__ __forceinline__ void operator()(const f32x4 (&acc)[2][2][4][2], const Unit& u, int wr, int wc, int fr, int fq) const {
;         int row0 = u.pm * BM + wr * 64 + fr, col0 = u.pn * BM + wc * 32 + 8 * fq;
;         asm volatile("" : "+v"(row0), "+v"(col0));
;         u32x4 gw[2][2][2], tw[2][2][2];
; #pragma unroll
;         for (int ch = 0; ch <= 4; ++ch) {
;             if (ch < 4) {
; #pragma unroll
;                 for (int mm = 0; mm < 2; ++mm) { const size_t row = (size_t)(row0 + (ch >> 1) * HALF + ((ch & 1) * 2 + mm) * 16);
; #pragma unroll
;                     for (int bj = 0; bj < 2; ++bj) { const int c = col0 + bj * HALF;
;                         gw[ch & 1][mm][bj] = *(const u32x4*)(G + row * 4096 + (SECOND ? 2048 : 0) + c);
;                         if (SECOND) tw[ch & 1][mm][bj] = *(const u32x4*)(T + row * 2048 + c); } }
;             }
;             asm volatile("" ::: "memory");
;             if (ch > 0) {
;                 const int pc = ch - 1, ai = pc >> 1;
; #pragma unroll
;                 for (int mm = 0; mm < 2; ++mm) { const int m = (pc & 1) * 2 + mm; const size_t row = (size_t)(row0 + ai * HALF + m * 16);
; #pragma unroll
;                     for (int bj = 0; bj < 2; ++bj) { const int c = col0 + bj * HALF;
;                         const f32x4 a0 = acc[ai][bj][m][0], a1 = acc[ai][bj][m][1];
;                         float o[8];
; #pragma unroll
;                         for (int e = 0; e < 4; ++e) {
;                             const unsigned gwe = gw[pc & 1][mm][bj][e], twe = SECOND ? tw[pc & 1][mm][bj][e] : 0u;
;                             const float glo = __uint_as_float(gwe << 16), ghi = __uint_as_float(gwe & 0xffff0000u);
;                             const float tlo = __uint_as_float(twe << 16), thi = __uint_as_float(twe & 0xffff0000u);
;                             const float alo = (e < 2) ? a0[2 * e] : a1[2 * e - 4], ahi = (e < 2) ? a0[2 * e + 1] : a1[2 * e - 3];
;                             o[2 * e] = tlo + glo * alo; o[2 * e + 1] = thi + ghi * ahi;
;                         }
;                         u32x4 w; w.x = cvt_pk_bf16(o[0], o[1]); w.y = cvt_pk_bf16(o[2], o[3]); w.z = cvt_pk_bf16(o[4], o[5]); w.w = cvt_pk_bf16(o[6], o[7]);
;                         *(u32x4*)(T + row * 2048 + c) = w;
.LBB0_485:
	v_mov_b32_e32 v240, s57
	v_lshlrev_b32_e32 v240, 17, v240
	v_lshl_add_u32 v240, s46, 21, v240
	v_lshrrev_b32_e32 v232, 6, v189
	v_lshl_add_u32 v240, v232, 14, v240
	v_lshl_add_u32 v232, v188, 4, v240
	v_add_u32_e32 v233, 0x1000, v232
	v_add_u32_e32 v234, 0x2000, v232
	v_add_u32_e32 v235, 0x3000, v232
	v_mov_b32_e32 v240, s57
	v_lshlrev_b32_e32 v240, 17, v240
	v_lshl_add_u32 v240, s46, 20, v240
	v_lshrrev_b32_e32 v236, 6, v189
	v_lshl_add_u32 v240, v236, 14, v240
	v_lshl_add_u32 v236, v188, 4, v240
	v_add_u32_e32 v237, 0x1000, v236
	v_add_u32_e32 v238, 0x2000, v236
	v_add_u32_e32 v239, 0x3000, v236
	v_lshl_add_u32 v134, s46, 8, v142
	v_lshl_or_b32 v132, s57, 8, v143
	v_readlane_b32 s6, v254, 44
	v_ashrrev_i32_e32 v135, 31, v134
	v_ashrrev_i32_e32 v133, 31, v132
	v_lshlrev_b64 v[136:137], 13, v[134:135]
	v_lshl_add_u64 v[136:137], s[70:71], 0, v[136:137]
	v_lshlrev_b64 v[132:133], 1, v[132:133]
	v_add_u32_e32 v166, 16, v134
	v_lshl_add_u64 v[136:137], v[136:137], 0, v[132:133]
	v_ashrrev_i32_e32 v167, 31, v166
	global_load_dwordx4 v[150:153], v232, s[70:71]
	global_load_dwordx4 v[154:157], v232, s[70:71] offset:1024
	v_lshlrev_b64 v[136:137], 13, v[166:167]
	v_lshl_add_u64 v[136:137], s[70:71], 0, v[136:137]
	v_lshl_add_u64 v[136:137], v[136:137], 0, v[132:133]
	global_load_dwordx4 v[158:161], v232, s[70:71] offset:2048
	global_load_dwordx4 v[162:165], v232, s[70:71] offset:3072
	v_add_u32_e32 v174, 32, v134
	v_add_u32_e32 v136, 48, v134
	v_ashrrev_i32_e32 v175, 31, v174
	v_ashrrev_i32_e32 v137, 31, v136
	v_lshlrev_b64 v[170:171], 13, v[174:175]
	v_lshlrev_b64 v[172:173], 13, v[136:137]
	v_lshlrev_b64 v[168:169], 12, v[134:135]
	v_readlane_b32 s7, v254, 45
	v_lshl_add_u64 v[170:171], s[70:71], 0, v[170:171]
	v_lshl_add_u64 v[172:173], s[70:71], 0, v[172:173]
	v_lshl_add_u64 v[168:169], s[6:7], 0, v[168:169]
	v_lshlrev_b64 v[166:167], 12, v[166:167]
	v_lshl_add_u64 v[170:171], v[170:171], 0, v[132:133]
	v_lshl_add_u64 v[184:185], v[172:173], 0, v[132:133]
	v_lshl_add_u64 v[190:191], v[168:169], 0, v[132:133]
	v_lshl_add_u64 v[192:193], s[6:7], 0, v[166:167]
	global_load_dwordx4 v[166:169], v233, s[70:71]
	s_nop 0
	global_load_dwordx4 v[170:173], v233, s[70:71] offset:1024
	s_nop 0
	global_load_dwordx4 v[180:183], v233, s[70:71] offset:2048
	s_nop 0
	global_load_dwordx4 v[184:187], v233, s[70:71] offset:3072
	s_andn2_b64 vcc, exec, s[0:1]
	s_mov_b64 s[0:1], -1
	s_waitcnt vmcnt(7)
	v_lshlrev_b32_e32 v194, 16, v150
	v_and_b32_e32 v195, 0xffff0000, v150
	v_lshlrev_b32_e32 v150, 16, v151
	v_and_b32_e32 v151, 0xffff0000, v151
	s_waitcnt vmcnt(6)
	v_lshlrev_b32_e32 v200, 16, v154
	v_and_b32_e32 v201, 0xffff0000, v154
	v_lshlrev_b32_e32 v154, 16, v155
	v_and_b32_e32 v155, 0xffff0000, v155
	v_lshlrev_b32_e32 v202, 16, v156
	v_and_b32_e32 v203, 0xffff0000, v156
	v_lshlrev_b32_e32 v156, 16, v157
	v_and_b32_e32 v157, 0xffff0000, v157
	v_lshlrev_b32_e32 v198, 16, v152
	v_and_b32_e32 v199, 0xffff0000, v152
	v_lshlrev_b32_e32 v152, 16, v153
	v_and_b32_e32 v153, 0xffff0000, v153
	v_pk_fma_f32 v[118:119], v[118:119], v[150:151], 0 op_sel_hi:[1,1,0]
	v_pk_fma_f32 v[126:127], v[126:127], v[154:155], 0 op_sel_hi:[1,1,0]
	v_pk_fma_f32 v[120:121], v[120:121], v[202:203], 0 op_sel_hi:[1,1,0]
	v_pk_fma_f32 v[122:123], v[122:123], v[156:157], 0 op_sel_hi:[1,1,0]
	s_waitcnt vmcnt(5)
	v_lshlrev_b32_e32 v154, 16, v158
	v_and_b32_e32 v155, 0xffff0000, v158
	v_lshlrev_b32_e32 v156, 16, v159
	v_and_b32_e32 v157, 0xffff0000, v159
	v_lshlrev_b32_e32 v158, 16, v160
	v_and_b32_e32 v159, 0xffff0000, v160
	v_lshlrev_b32_e32 v160, 16, v161
	v_and_b32_e32 v161, 0xffff0000, v161
	v_pk_fma_f32 v[116:117], v[116:117], v[194:195], 0 op_sel_hi:[1,1,0]
	v_pk_fma_f32 v[150:151], v[112:113], v[198:199], 0 op_sel_hi:[1,1,0]
	v_pk_fma_f32 v[152:153], v[114:115], v[152:153], 0 op_sel_hi:[1,1,0]
	v_cvt_pk_bf16_f32 v113, v118, v119
	v_cvt_pk_bf16_f32 v118, v120, v121
	v_cvt_pk_bf16_f32 v119, v122, v123
	v_pk_fma_f32 v[108:109], v[108:109], v[154:155], 0 op_sel_hi:[1,1,0]
	v_pk_fma_f32 v[110:111], v[110:111], v[156:157], 0 op_sel_hi:[1,1,0]
	v_pk_fma_f32 v[120:121], v[104:105], v[158:159], 0 op_sel_hi:[1,1,0]
	v_pk_fma_f32 v[122:123], v[106:107], v[160:161], 0 op_sel_hi:[1,1,0]
	v_pk_fma_f32 v[124:125], v[124:125], v[200:201], 0 op_sel_hi:[1,1,0]
	v_cvt_pk_bf16_f32 v112, v116, v117
	v_cvt_pk_bf16_f32 v114, v150, v151
	v_cvt_pk_bf16_f32 v115, v152, v153
	v_cvt_pk_bf16_f32 v104, v108, v109
	v_cvt_pk_bf16_f32 v105, v110, v111
	v_cvt_pk_bf16_f32 v106, v120, v121
	v_cvt_pk_bf16_f32 v107, v122, v123
	v_lshl_add_u64 v[108:109], v[192:193], 0, v[132:133]
	v_cvt_pk_bf16_f32 v116, v124, v125
	v_cvt_pk_bf16_f32 v117, v126, v127
	global_store_dwordx4 v236, v[112:115], s[6:7]
	global_store_dwordx4 v236, v[116:119], s[6:7] offset:1024
	global_store_dwordx4 v236, v[104:107], s[6:7] offset:2048
	v_add_u32_e32 v112, 0x80, v134
	v_ashrrev_i32_e32 v113, 31, v112
	s_waitcnt vmcnt(7)
	v_lshlrev_b32_e32 v104, 16, v162
	v_and_b32_e32 v105, 0xffff0000, v162
	v_pk_fma_f32 v[100:101], v[100:101], v[104:105], 0 op_sel_hi:[1,1,0]
	v_lshlrev_b32_e32 v104, 16, v163
	v_and_b32_e32 v105, 0xffff0000, v163
	v_pk_fma_f32 v[102:103], v[102:103], v[104:105], 0 op_sel_hi:[1,1,0]
	v_lshlrev_b32_e32 v104, 16, v164
	v_and_b32_e32 v105, 0xffff0000, v164
	v_pk_fma_f32 v[104:105], v[96:97], v[104:105], 0 op_sel_hi:[1,1,0]
	v_lshlrev_b32_e32 v96, 16, v165
	v_and_b32_e32 v97, 0xffff0000, v165
	v_pk_fma_f32 v[106:107], v[98:99], v[96:97], 0 op_sel_hi:[1,1,0]
	v_cvt_pk_bf16_f32 v96, v100, v101
	v_cvt_pk_bf16_f32 v97, v102, v103
	v_cvt_pk_bf16_f32 v98, v104, v105
	v_cvt_pk_bf16_f32 v99, v106, v107
	global_store_dwordx4 v236, v[96:99], s[6:7] offset:3072
	s_waitcnt vmcnt(7)
; __device__ __forceinline__ unsigned cvt_pk_bf16(float lo, float hi) { typedef float f2_t __attribute__((ext_vector_type(2))); typedef __bf16 b2_t __attribute__((ext_vector_type(2))); const f2_t v = {lo, hi}; return __builtin_bit_cast(unsigned, __builtin_convertvector(v, b2_t)); }
;     __device__ __forceinline__ void operator()(const f32x4 (&acc)[2][2][4][2], const Unit& u, int wr, int wc, int fr, int fq) const {
;     ...
;         for (int ch = 0; ch <= 4; ++ch) {
;             if (ch < 4) {
; #pragma unroll
;                 for (int mm = 0; mm < 2; ++mm) { const size_t row = (size_t)(row0 + (ch >> 1) * HALF + ((ch & 1) * 2 + mm) * 16);
; #pragma unroll
;                     for (int bj = 0; bj < 2; ++bj) { const int c = col0 + bj * HALF;
;                         gw[ch & 1][mm][bj] = *(const u32x4*)(G + row * 4096 + (SECOND ? 2048 : 0) + c);
;                         if (SECOND) tw[ch & 1][mm][bj] = *(const u32x4*)(T + row * 2048 + c); } }
;             }
;             asm volatile("" ::: "memory");
;             if (ch > 0) {
;                 const int pc = ch - 1, ai = pc >> 1;
; #pragma unroll
;                 for (int mm = 0; mm < 2; ++mm) { const int m = (pc & 1) * 2 + mm; const size_t row = (size_t)(row0 + ai * HALF + m * 16);
; #pragma unroll
;                     for (int bj = 0; bj < 2; ++bj) { const int c = col0 + bj * HALF;
;                         const f32x4 a0 = acc[ai][bj][m][0], a1 = acc[ai][bj][m][1];
;                         float o[8];
; #pragma unroll
;                         for (int e = 0; e < 4; ++e) {
;                             const unsigned gwe = gw[pc & 1][mm][bj][e], twe = SECOND ? tw[pc & 1][mm][bj][e] : 0u;
;                             const float glo = __uint_as_float(gwe << 16), ghi = __uint_as_float(gwe & 0xffff0000u);
;                             const float tlo = __uint_as_float(twe << 16), thi = __uint_as_float(twe & 0xffff0000u);
;                             const float alo = (e < 2) ? a0[2 * e] : a1[2 * e - 4], ahi = (e < 2) ? a0[2 * e + 1] : a1[2 * e - 3];
;                             o[2 * e] = tlo + glo * alo; o[2 * e + 1] = thi + ghi * ahi;
;                         }
;                         u32x4 w; w.x = cvt_pk_bf16(o[0], o[1]); w.y = cvt_pk_bf16(o[2], o[3]); w.z = cvt_pk_bf16(o[4], o[5]); w.w = cvt_pk_bf16(o[6], o[7]);
;                         *(u32x4*)(T + row * 2048 + c) = w;
	v_lshlrev_b32_e32 v118, 16, v166
	v_and_b32_e32 v119, 0xffff0000, v166
	v_lshlrev_b64 v[96:97], 13, v[112:113]
	v_lshl_add_u64 v[96:97], s[70:71], 0, v[96:97]
	v_add_u32_e32 v114, 0x90, v134
	v_pk_fma_f32 v[92:93], v[92:93], v[118:119], 0 op_sel_hi:[1,1,0]
	v_lshlrev_b32_e32 v118, 16, v167
	v_and_b32_e32 v119, 0xffff0000, v167
	v_lshl_add_u64 v[96:97], v[96:97], 0, v[132:133]
	v_ashrrev_i32_e32 v115, 31, v114
	v_pk_fma_f32 v[94:95], v[94:95], v[118:119], 0 op_sel_hi:[1,1,0]
	v_lshlrev_b32_e32 v118, 16, v168
	v_and_b32_e32 v119, 0xffff0000, v168
	global_load_dwordx4 v[100:103], v234, s[70:71]
	global_load_dwordx4 v[104:107], v234, s[70:71] offset:1024
	v_lshlrev_b64 v[96:97], 13, v[114:115]
	v_lshlrev_b64 v[116:117], 12, v[174:175]
	v_pk_fma_f32 v[118:119], v[88:89], v[118:119], 0 op_sel_hi:[1,1,0]
	v_lshlrev_b32_e32 v88, 16, v169
	v_and_b32_e32 v89, 0xffff0000, v169
	v_lshl_add_u64 v[96:97], s[70:71], 0, v[96:97]
	v_pk_fma_f32 v[120:121], v[90:91], v[88:89], 0 op_sel_hi:[1,1,0]
	v_cvt_pk_bf16_f32 v88, v92, v93
	v_lshl_add_u64 v[92:93], s[6:7], 0, v[116:117]
	v_lshl_add_u64 v[96:97], v[96:97], 0, v[132:133]
	v_cvt_pk_bf16_f32 v89, v94, v95
	v_cvt_pk_bf16_f32 v90, v118, v119
	v_cvt_pk_bf16_f32 v91, v120, v121
	v_lshl_add_u64 v[92:93], v[92:93], 0, v[132:133]
	global_load_dwordx4 v[108:111], v234, s[70:71] offset:2048
	s_nop 0
	global_load_dwordx4 v[96:99], v234, s[70:71] offset:3072
	global_store_dwordx4 v237, v[88:91], s[6:7]
	s_waitcnt vmcnt(11)
	s_nop 0
	v_lshlrev_b32_e32 v88, 16, v170
	v_and_b32_e32 v89, 0xffff0000, v170
	v_pk_fma_f32 v[84:85], v[84:85], v[88:89], 0 op_sel_hi:[1,1,0]
	v_lshlrev_b32_e32 v88, 16, v171
	v_and_b32_e32 v89, 0xffff0000, v171
	v_pk_fma_f32 v[86:87], v[86:87], v[88:89], 0 op_sel_hi:[1,1,0]
	v_lshlrev_b32_e32 v88, 16, v172
	v_and_b32_e32 v89, 0xffff0000, v172
	v_pk_fma_f32 v[88:89], v[80:81], v[88:89], 0 op_sel_hi:[1,1,0]
	v_lshlrev_b32_e32 v80, 16, v173
	v_and_b32_e32 v81, 0xffff0000, v173
	v_pk_fma_f32 v[90:91], v[82:83], v[80:81], 0 op_sel_hi:[1,1,0]
	v_cvt_pk_bf16_f32 v80, v84, v85
	v_cvt_pk_bf16_f32 v81, v86, v87
	v_cvt_pk_bf16_f32 v82, v88, v89
	v_cvt_pk_bf16_f32 v83, v90, v91
	global_store_dwordx4 v237, v[80:83], s[6:7] offset:1024
	s_waitcnt vmcnt(5)
	v_lshlrev_b32_e32 v86, 16, v100
	v_lshlrev_b32_e32 v82, 16, v180
	v_and_b32_e32 v83, 0xffff0000, v180
	v_pk_fma_f32 v[76:77], v[76:77], v[82:83], 0 op_sel_hi:[1,1,0]
	v_lshlrev_b32_e32 v82, 16, v181
	v_and_b32_e32 v83, 0xffff0000, v181
	v_pk_fma_f32 v[78:79], v[78:79], v[82:83], 0 op_sel_hi:[1,1,0]
	v_lshlrev_b32_e32 v82, 16, v182
	v_and_b32_e32 v83, 0xffff0000, v182
	v_lshlrev_b64 v[80:81], 12, v[136:137]
	v_pk_fma_f32 v[82:83], v[72:73], v[82:83], 0 op_sel_hi:[1,1,0]
	v_lshlrev_b32_e32 v72, 16, v183
	v_and_b32_e32 v73, 0xffff0000, v183
	v_pk_fma_f32 v[84:85], v[74:75], v[72:73], 0 op_sel_hi:[1,1,0]
	v_cvt_pk_bf16_f32 v72, v76, v77
	v_lshl_add_u64 v[76:77], s[6:7], 0, v[80:81]
	v_cvt_pk_bf16_f32 v73, v78, v79
	v_cvt_pk_bf16_f32 v74, v82, v83
	v_cvt_pk_bf16_f32 v75, v84, v85
	v_lshl_add_u64 v[76:77], v[76:77], 0, v[132:133]
	global_store_dwordx4 v237, v[72:75], s[6:7] offset:2048
	v_add_u32_e32 v80, 0xa0, v134
	v_ashrrev_i32_e32 v81, 31, v80
	v_lshlrev_b32_e32 v72, 16, v184
	v_and_b32_e32 v73, 0xffff0000, v184
	v_pk_fma_f32 v[68:69], v[68:69], v[72:73], 0 op_sel_hi:[1,1,0]
	v_lshlrev_b32_e32 v72, 16, v185
	v_and_b32_e32 v73, 0xffff0000, v185
	v_pk_fma_f32 v[70:71], v[70:71], v[72:73], 0 op_sel_hi:[1,1,0]
	v_lshlrev_b32_e32 v72, 16, v186
	v_and_b32_e32 v73, 0xffff0000, v186
	v_pk_fma_f32 v[72:73], v[64:65], v[72:73], 0 op_sel_hi:[1,1,0]
	v_lshlrev_b32_e32 v64, 16, v187
	v_and_b32_e32 v65, 0xffff0000, v187
	v_pk_fma_f32 v[74:75], v[66:67], v[64:65], 0 op_sel_hi:[1,1,0]
	v_cvt_pk_bf16_f32 v64, v68, v69
	v_cvt_pk_bf16_f32 v65, v70, v71
	v_cvt_pk_bf16_f32 v66, v72, v73
	v_cvt_pk_bf16_f32 v67, v74, v75
	global_store_dwordx4 v237, v[64:67], s[6:7] offset:3072
	v_add_u32_e32 v82, 0xb0, v134
	v_ashrrev_i32_e32 v83, 31, v82
	v_lshlrev_b64 v[64:65], 13, v[80:81]
	v_lshl_add_u64 v[64:65], s[70:71], 0, v[64:65]
	v_lshl_add_u64 v[64:65], v[64:65], 0, v[132:133]
	global_load_dwordx4 v[68:71], v235, s[70:71]
	global_load_dwordx4 v[72:75], v235, s[70:71] offset:1024
	v_lshlrev_b64 v[64:65], 13, v[82:83]
	v_lshl_add_u64 v[64:65], s[70:71], 0, v[64:65]
	v_lshl_add_u64 v[64:65], v[64:65], 0, v[132:133]
	global_load_dwordx4 v[76:79], v235, s[70:71] offset:2048
	s_nop 0
	global_load_dwordx4 v[64:67], v235, s[70:71] offset:3072
	v_and_b32_e32 v87, 0xffff0000, v100
	v_pk_fma_f32 v[60:61], v[60:61], v[86:87], 0 op_sel_hi:[1,1,0]
	v_lshlrev_b32_e32 v86, 16, v101
	v_and_b32_e32 v87, 0xffff0000, v101
	v_pk_fma_f32 v[62:63], v[62:63], v[86:87], 0 op_sel_hi:[1,1,0]
	v_lshlrev_b32_e32 v86, 16, v102
	v_and_b32_e32 v87, 0xffff0000, v102
	v_lshlrev_b64 v[84:85], 12, v[112:113]
	v_pk_fma_f32 v[86:87], v[56:57], v[86:87], 0 op_sel_hi:[1,1,0]
	v_lshlrev_b32_e32 v56, 16, v103
	v_and_b32_e32 v57, 0xffff0000, v103
	v_pk_fma_f32 v[88:89], v[58:59], v[56:57], 0 op_sel_hi:[1,1,0]
	v_cvt_pk_bf16_f32 v56, v60, v61
	v_lshl_add_u64 v[60:61], s[6:7], 0, v[84:85]
	v_cvt_pk_bf16_f32 v57, v62, v63
	v_cvt_pk_bf16_f32 v58, v86, v87
	v_cvt_pk_bf16_f32 v59, v88, v89
	v_lshl_add_u64 v[60:61], v[60:61], 0, v[132:133]
	global_store_dwordx4 v238, v[56:59], s[6:7]
	s_waitcnt vmcnt(11)
; __device__ __forceinline__ unsigned cvt_pk_bf16(float lo, float hi) { typedef float f2_t __attribute__((ext_vector_type(2))); typedef __bf16 b2_t __attribute__((ext_vector_type(2))); const f2_t v = {lo, hi}; return __builtin_bit_cast(unsigned, __builtin_convertvector(v, b2_t)); }
;     __device__ __forceinline__ void operator()(const f32x4 (&acc)[2][2][4][2], const Unit& u, int wr, int wc, int fr, int fq) const {
;     ...
;                 for (int mm = 0; mm < 2; ++mm) { const int m = (pc & 1) * 2 + mm; const size_t row = (size_t)(row0 + ai * HALF + m * 16);
; #pragma unroll
;                     for (int bj = 0; bj < 2; ++bj) { const int c = col0 + bj * HALF;
;                         const f32x4 a0 = acc[ai][bj][m][0], a1 = acc[ai][bj][m][1];
;                         float o[8];
; #pragma unroll
;                         for (int e = 0; e < 4; ++e) {
;                             const unsigned gwe = gw[pc & 1][mm][bj][e], twe = SECOND ? tw[pc & 1][mm][bj][e] : 0u;
;                             const float glo = __uint_as_float(gwe << 16), ghi = __uint_as_float(gwe & 0xffff0000u);
;                             const float tlo = __uint_as_float(twe << 16), thi = __uint_as_float(twe & 0xffff0000u);
;                             const float alo = (e < 2) ? a0[2 * e] : a1[2 * e - 4], ahi = (e < 2) ? a0[2 * e + 1] : a1[2 * e - 3];
;                             o[2 * e] = tlo + glo * alo; o[2 * e + 1] = thi + ghi * ahi;
;                         }
;                         u32x4 w; w.x = cvt_pk_bf16(o[0], o[1]); w.y = cvt_pk_bf16(o[2], o[3]); w.z = cvt_pk_bf16(o[4], o[5]); w.w = cvt_pk_bf16(o[6], o[7]);
;                         *(u32x4*)(T + row * 2048 + c) = w;
	s_nop 0
	v_lshlrev_b32_e32 v56, 16, v104
	v_and_b32_e32 v57, 0xffff0000, v104
	v_pk_fma_f32 v[52:53], v[52:53], v[56:57], 0 op_sel_hi:[1,1,0]
	v_lshlrev_b32_e32 v56, 16, v105
	v_and_b32_e32 v57, 0xffff0000, v105
	v_pk_fma_f32 v[54:55], v[54:55], v[56:57], 0 op_sel_hi:[1,1,0]
	v_lshlrev_b32_e32 v56, 16, v106
	v_and_b32_e32 v57, 0xffff0000, v106
	v_pk_fma_f32 v[56:57], v[48:49], v[56:57], 0 op_sel_hi:[1,1,0]
	v_lshlrev_b32_e32 v48, 16, v107
	v_and_b32_e32 v49, 0xffff0000, v107
	v_pk_fma_f32 v[58:59], v[50:51], v[48:49], 0 op_sel_hi:[1,1,0]
	v_cvt_pk_bf16_f32 v48, v52, v53
	v_cvt_pk_bf16_f32 v49, v54, v55
	v_cvt_pk_bf16_f32 v50, v56, v57
	v_cvt_pk_bf16_f32 v51, v58, v59
	global_store_dwordx4 v238, v[48:51], s[6:7] offset:1024
	s_waitcnt vmcnt(11)
	s_nop 0
	v_lshlrev_b32_e32 v50, 16, v108
	v_and_b32_e32 v51, 0xffff0000, v108
	v_pk_fma_f32 v[44:45], v[44:45], v[50:51], 0 op_sel_hi:[1,1,0]
	v_lshlrev_b32_e32 v50, 16, v109
	v_and_b32_e32 v51, 0xffff0000, v109
	v_pk_fma_f32 v[46:47], v[46:47], v[50:51], 0 op_sel_hi:[1,1,0]
	v_lshlrev_b32_e32 v50, 16, v110
	v_and_b32_e32 v51, 0xffff0000, v110
	v_lshlrev_b64 v[48:49], 12, v[114:115]
	v_pk_fma_f32 v[50:51], v[40:41], v[50:51], 0 op_sel_hi:[1,1,0]
	v_lshlrev_b32_e32 v40, 16, v111
	v_and_b32_e32 v41, 0xffff0000, v111
	v_pk_fma_f32 v[52:53], v[42:43], v[40:41], 0 op_sel_hi:[1,1,0]
	v_cvt_pk_bf16_f32 v40, v44, v45
	v_lshl_add_u64 v[44:45], s[6:7], 0, v[48:49]
	v_cvt_pk_bf16_f32 v41, v46, v47
	v_cvt_pk_bf16_f32 v42, v50, v51
	v_cvt_pk_bf16_f32 v43, v52, v53
	v_lshl_add_u64 v[44:45], v[44:45], 0, v[132:133]
	global_store_dwordx4 v238, v[40:43], s[6:7] offset:2048
	s_waitcnt vmcnt(11)
	s_nop 0
	v_lshlrev_b32_e32 v40, 16, v96
	v_and_b32_e32 v41, 0xffff0000, v96
	v_pk_fma_f32 v[36:37], v[36:37], v[40:41], 0 op_sel_hi:[1,1,0]
	v_lshlrev_b32_e32 v40, 16, v97
	v_and_b32_e32 v41, 0xffff0000, v97
	v_pk_fma_f32 v[38:39], v[38:39], v[40:41], 0 op_sel_hi:[1,1,0]
	v_lshlrev_b32_e32 v40, 16, v98
	v_and_b32_e32 v41, 0xffff0000, v98
	v_pk_fma_f32 v[40:41], v[32:33], v[40:41], 0 op_sel_hi:[1,1,0]
	v_lshlrev_b32_e32 v32, 16, v99
	v_and_b32_e32 v33, 0xffff0000, v99
	v_pk_fma_f32 v[42:43], v[34:35], v[32:33], 0 op_sel_hi:[1,1,0]
	v_cvt_pk_bf16_f32 v32, v36, v37
	v_cvt_pk_bf16_f32 v33, v38, v39
	v_cvt_pk_bf16_f32 v34, v40, v41
	v_cvt_pk_bf16_f32 v35, v42, v43
	global_store_dwordx4 v238, v[32:35], s[6:7] offset:3072
	s_waitcnt vmcnt(7)
	s_nop 0
	v_lshlrev_b32_e32 v34, 16, v68
	v_and_b32_e32 v35, 0xffff0000, v68
	v_pk_fma_f32 v[28:29], v[28:29], v[34:35], 0 op_sel_hi:[1,1,0]
	v_lshlrev_b32_e32 v34, 16, v69
	v_and_b32_e32 v35, 0xffff0000, v69
	v_pk_fma_f32 v[30:31], v[30:31], v[34:35], 0 op_sel_hi:[1,1,0]
	v_lshlrev_b32_e32 v34, 16, v70
	v_and_b32_e32 v35, 0xffff0000, v70
	v_lshlrev_b64 v[32:33], 12, v[80:81]
	v_pk_fma_f32 v[34:35], v[24:25], v[34:35], 0 op_sel_hi:[1,1,0]
	v_lshlrev_b32_e32 v24, 16, v71
	v_and_b32_e32 v25, 0xffff0000, v71
	v_pk_fma_f32 v[36:37], v[26:27], v[24:25], 0 op_sel_hi:[1,1,0]
	v_cvt_pk_bf16_f32 v24, v28, v29
	v_lshl_add_u64 v[28:29], s[6:7], 0, v[32:33]
	v_cvt_pk_bf16_f32 v25, v30, v31
	v_cvt_pk_bf16_f32 v26, v34, v35
	v_cvt_pk_bf16_f32 v27, v36, v37
	v_lshl_add_u64 v[28:29], v[28:29], 0, v[132:133]
	global_store_dwordx4 v239, v[24:27], s[6:7]
	s_waitcnt vmcnt(7)
	s_nop 0
	v_lshlrev_b32_e32 v24, 16, v72
	v_and_b32_e32 v25, 0xffff0000, v72
	v_pk_fma_f32 v[20:21], v[20:21], v[24:25], 0 op_sel_hi:[1,1,0]
	v_lshlrev_b32_e32 v24, 16, v73
	v_and_b32_e32 v25, 0xffff0000, v73
	v_pk_fma_f32 v[22:23], v[22:23], v[24:25], 0 op_sel_hi:[1,1,0]
	v_lshlrev_b32_e32 v24, 16, v74
	v_and_b32_e32 v25, 0xffff0000, v74
	v_pk_fma_f32 v[24:25], v[16:17], v[24:25], 0 op_sel_hi:[1,1,0]
	v_lshlrev_b32_e32 v16, 16, v75
	v_and_b32_e32 v17, 0xffff0000, v75
	v_pk_fma_f32 v[26:27], v[18:19], v[16:17], 0 op_sel_hi:[1,1,0]
	v_cvt_pk_bf16_f32 v16, v20, v21
	v_cvt_pk_bf16_f32 v17, v22, v23
	v_cvt_pk_bf16_f32 v18, v24, v25
	v_cvt_pk_bf16_f32 v19, v26, v27
	global_store_dwordx4 v239, v[16:19], s[6:7] offset:1024
	s_waitcnt vmcnt(7)
	s_nop 0
	v_lshlrev_b32_e32 v18, 16, v76
	v_and_b32_e32 v19, 0xffff0000, v76
	v_pk_fma_f32 v[12:13], v[12:13], v[18:19], 0 op_sel_hi:[1,1,0]
	v_lshlrev_b32_e32 v18, 16, v77
	v_and_b32_e32 v19, 0xffff0000, v77
	v_pk_fma_f32 v[14:15], v[14:15], v[18:19], 0 op_sel_hi:[1,1,0]
	v_lshlrev_b32_e32 v18, 16, v78
	v_and_b32_e32 v19, 0xffff0000, v78
	v_lshlrev_b64 v[16:17], 12, v[82:83]
	v_pk_fma_f32 v[18:19], v[8:9], v[18:19], 0 op_sel_hi:[1,1,0]
	v_lshlrev_b32_e32 v8, 16, v79
	v_and_b32_e32 v9, 0xffff0000, v79
	v_pk_fma_f32 v[20:21], v[10:11], v[8:9], 0 op_sel_hi:[1,1,0]
	v_cvt_pk_bf16_f32 v8, v12, v13
	v_lshl_add_u64 v[12:13], s[6:7], 0, v[16:17]
	v_cvt_pk_bf16_f32 v9, v14, v15
	v_cvt_pk_bf16_f32 v10, v18, v19
	v_cvt_pk_bf16_f32 v11, v20, v21
	v_lshl_add_u64 v[12:13], v[12:13], 0, v[132:133]
	global_store_dwordx4 v239, v[8:11], s[6:7] offset:2048
	s_waitcnt vmcnt(7)
	s_nop 0
	v_lshlrev_b32_e32 v8, 16, v64
	v_and_b32_e32 v9, 0xffff0000, v64
	v_pk_fma_f32 v[4:5], v[4:5], v[8:9], 0 op_sel_hi:[1,1,0]
	v_lshlrev_b32_e32 v8, 16, v65
	v_and_b32_e32 v9, 0xffff0000, v65
	v_pk_fma_f32 v[6:7], v[6:7], v[8:9], 0 op_sel_hi:[1,1,0]
	v_lshlrev_b32_e32 v8, 16, v66
	v_and_b32_e32 v9, 0xffff0000, v66
	v_pk_fma_f32 v[8:9], v[0:1], v[8:9], 0 op_sel_hi:[1,1,0]
	v_lshlrev_b32_e32 v0, 16, v67
	v_and_b32_e32 v1, 0xffff0000, v67
	v_pk_fma_f32 v[10:11], v[2:3], v[0:1], 0 op_sel_hi:[1,1,0]
	v_cvt_pk_bf16_f32 v0, v4, v5
	v_cvt_pk_bf16_f32 v1, v6, v7
	v_cvt_pk_bf16_f32 v2, v8, v9
	v_cvt_pk_bf16_f32 v3, v10, v11
	global_store_dwordx4 v239, v[0:3], s[6:7] offset:3072
	s_cbranch_vccnz .LBB0_474
	s_andn2_b64 vcc, exec, s[12:13]
	s_cbranch_vccnz .LBB0_473
	s_barrier
	s_branch .LBB0_473

; __device__ __forceinline__ unsigned cvt_pk_bf16(float lo, float hi) { typedef float f2_t __attribute__((ext_vector_type(2))); typedef __bf16 b2_t __attribute__((ext_vector_type(2))); const f2_t v = {lo, hi}; return __builtin_bit_cast(unsigned, __builtin_convertvector(v, b2_t)); }
;     __device__ __forceinline__ void operator()(const f32x4 (&acc)[2][2][4][2], const Unit& u, int wr, int wc, int fr, int fq) const {
;     ...
;         for (int ch = 0; ch <= 4; ++ch) {
;             if (ch < 4) {
; #pragma unroll
;                 for (int mm = 0; mm < 2; ++mm) { const size_t row = (size_t)(row0 + (ch >> 1) * HALF + ((ch & 1) * 2 + mm) * 16);
; #pragma unroll
;                     for (int bj = 0; bj < 2; ++bj) { const int c = col0 + bj * HALF;
;                         gw[ch & 1][mm][bj] = *(const u32x4*)(G + row * 4096 + (SECOND ? 2048 : 0) + c);
;                         if (SECOND) tw[ch & 1][mm][bj] = *(const u32x4*)(T + row * 2048 + c); } }
;             }
;             asm volatile("" ::: "memory");
;             if (ch > 0) {
;                 const int pc = ch - 1, ai = pc >> 1;
; #pragma unroll
;                 for (int mm = 0; mm < 2; ++mm) { const int m = (pc & 1) * 2 + mm; const size_t row = (size_t)(row0 + ai * HALF + m * 16);
; #pragma unroll
;                     for (int bj = 0; bj < 2; ++bj) { const int c = col0 + bj * HALF;
;                         const f32x4 a0 = acc[ai][bj][m][0], a1 = acc[ai][bj][m][1];
;                         float o[8];
; #pragma unroll
;                         for (int e = 0; e < 4; ++e) {
;                             const unsigned gwe = gw[pc & 1][mm][bj][e], twe = SECOND ? tw[pc & 1][mm][bj][e] : 0u;
;                             const float glo = __uint_as_float(gwe << 16), ghi = __uint_as_float(gwe & 0xffff0000u);
;                             const float tlo = __uint_as_float(twe << 16), thi = __uint_as_float(twe & 0xffff0000u);
;                             const float alo = (e < 2) ? a0[2 * e] : a1[2 * e - 4], ahi = (e < 2) ? a0[2 * e + 1] : a1[2 * e - 3];
;                             o[2 * e] = tlo + glo * alo; o[2 * e + 1] = thi + ghi * ahi;
;                         }
;                         u32x4 w; w.x = cvt_pk_bf16(o[0], o[1]); w.y = cvt_pk_bf16(o[2], o[3]); w.z = cvt_pk_bf16(o[4], o[5]); w.w = cvt_pk_bf16(o[6], o[7]);
;                         *(u32x4*)(T + row * 2048 + c) = w;
.LBB0_509:
	v_readlane_b32 s62, v254, 44
	v_readlane_b32 s63, v254, 45
	v_mov_b32_e32 v240, s58
	v_add_u32_e32 v240, 8, v240
	v_lshlrev_b32_e32 v240, 17, v240
	v_lshl_add_u32 v240, s46, 21, v240
	v_lshrrev_b32_e32 v232, 6, v189
	v_lshl_add_u32 v240, v232, 14, v240
	v_lshl_add_u32 v232, v188, 4, v240
	v_add_u32_e32 v233, 0x1000, v232
	v_add_u32_e32 v234, 0x2000, v232
	v_add_u32_e32 v235, 0x3000, v232
	v_mov_b32_e32 v240, s58
	v_lshlrev_b32_e32 v240, 17, v240
	v_lshl_add_u32 v240, s46, 20, v240
	v_lshrrev_b32_e32 v236, 6, v189
	v_lshl_add_u32 v240, v236, 14, v240
	v_lshl_add_u32 v236, v188, 4, v240
	v_add_u32_e32 v237, 0x1000, v236
	v_add_u32_e32 v238, 0x2000, v236
	v_add_u32_e32 v239, 0x3000, v236
	v_lshl_add_u32 v164, s46, 8, v180
	v_lshl_or_b32 v128, s58, 8, v181
	v_readlane_b32 s6, v254, 46
	v_ashrrev_i32_e32 v165, 31, v164
	v_ashrrev_i32_e32 v129, 31, v128
	v_lshlrev_b64 v[130:131], 13, v[164:165]
	v_lshl_add_u64 v[130:131], s[70:71], 0, v[130:131]
	v_lshlrev_b64 v[166:167], 1, v[128:129]
	v_lshlrev_b64 v[132:133], 12, v[164:165]
	v_readlane_b32 s7, v254, 47
	v_lshl_add_u64 v[128:129], v[130:131], 0, v[166:167]
	v_add_co_u32_e32 v130, vcc, 0x1000, v128
	v_lshl_add_u64 v[132:133], s[6:7], 0, v[132:133]
	v_lshl_add_u64 v[170:171], v[132:133], 0, v[166:167]
	v_addc_co_u32_e32 v131, vcc, 0, v129, vcc
	global_load_dwordx4 v[190:193], v236, s[62:63]
	global_load_dwordx4 v[206:209], v236, s[62:63] offset:1024
	global_load_dwordx4 v[198:201], v232, s[70:71]
	v_lshl_add_u64 v[128:129], v[128:129], 0, s[14:15]
	global_load_dwordx4 v[202:205], v232, s[70:71] offset:1024
	v_add_u32_e32 v130, 16, v164
	v_ashrrev_i32_e32 v131, 31, v130
	v_lshlrev_b64 v[134:135], 13, v[130:131]
	v_lshlrev_b64 v[130:131], 12, v[130:131]
	v_lshl_add_u64 v[134:135], s[70:71], 0, v[134:135]
	v_lshl_add_u64 v[130:131], s[6:7], 0, v[130:131]
	v_lshl_add_u64 v[134:135], v[134:135], 0, v[166:167]
	v_lshl_add_u64 v[174:175], v[130:131], 0, v[166:167]
	v_add_co_u32_e32 v130, vcc, s57, v134
	global_load_dwordx4 v[214:217], v236, s[62:63] offset:2048
	global_load_dwordx4 v[218:221], v236, s[62:63] offset:3072
	v_addc_co_u32_e32 v131, vcc, 0, v135, vcc
	global_load_dwordx4 v[210:213], v232, s[70:71] offset:2048
	v_add_u32_e32 v132, 48, v164
	v_ashrrev_i32_e32 v133, 31, v132
	v_lshlrev_b64 v[138:139], 13, v[132:133]
	v_lshlrev_b64 v[132:133], 12, v[132:133]
	v_lshl_add_u64 v[132:133], s[6:7], 0, v[132:133]
	v_lshl_add_u64 v[168:169], v[132:133], 0, v[166:167]
	v_lshl_add_u64 v[132:133], v[134:135], 0, s[14:15]
	global_load_dwordx4 v[222:225], v232, s[70:71] offset:3072
	v_add_u32_e32 v128, 32, v164
	v_ashrrev_i32_e32 v129, 31, v128
	v_lshlrev_b64 v[136:137], 13, v[128:129]
	v_lshl_add_u64 v[136:137], s[70:71], 0, v[136:137]
	v_lshlrev_b64 v[128:129], 12, v[128:129]
	v_lshl_add_u64 v[130:131], v[136:137], 0, v[166:167]
	v_lshl_add_u64 v[128:129], s[6:7], 0, v[128:129]
	v_lshl_add_u64 v[138:139], s[70:71], 0, v[138:139]
	v_lshl_add_u64 v[134:135], v[130:131], 0, s[14:15]
	v_add_co_u32_e32 v130, vcc, s57, v130
	v_lshl_add_u64 v[172:173], v[128:129], 0, v[166:167]
	v_lshl_add_u64 v[128:129], v[138:139], 0, v[166:167]
	v_addc_co_u32_e32 v131, vcc, 0, v131, vcc
	v_lshl_add_u64 v[136:137], v[128:129], 0, s[14:15]
	v_add_co_u32_e32 v128, vcc, s57, v128
	s_waitcnt vmcnt(7)
	v_lshlrev_b32_e32 v194, 16, v190
	v_addc_co_u32_e32 v129, vcc, 0, v129, vcc
	global_load_dwordx4 v[156:159], v233, s[70:71]
	global_load_dwordx4 v[148:151], v233, s[70:71] offset:1024
	global_load_dwordx4 v[152:155], v237, s[62:63]
	global_load_dwordx4 v[144:147], v237, s[62:63] offset:1024
	global_load_dwordx4 v[140:143], v233, s[70:71] offset:2048
	s_nop 0
	global_load_dwordx4 v[132:135], v233, s[70:71] offset:3072
	s_nop 0
	global_load_dwordx4 v[136:139], v237, s[62:63] offset:2048
	global_load_dwordx4 v[128:131], v237, s[62:63] offset:3072
	v_and_b32_e32 v195, 0xffff0000, v190
	v_lshlrev_b32_e32 v190, 16, v191
	v_and_b32_e32 v191, 0xffff0000, v191
	v_lshlrev_b32_e32 v226, 16, v192
	v_and_b32_e32 v227, 0xffff0000, v192
	s_waitcnt vmcnt(13)
	v_lshlrev_b32_e32 v228, 16, v198
	v_and_b32_e32 v229, 0xffff0000, v198
	v_lshlrev_b32_e32 v198, 16, v199
	v_and_b32_e32 v199, 0xffff0000, v199
	v_lshlrev_b32_e32 v230, 16, v200
	v_and_b32_e32 v231, 0xffff0000, v200
	v_pk_fma_f32 v[126:127], v[126:127], v[198:199], v[190:191]
	v_pk_fma_f32 v[190:191], v[120:121], v[230:231], v[226:227]
	v_lshlrev_b32_e32 v120, 16, v201
	v_and_b32_e32 v121, 0xffff0000, v201
	v_lshlrev_b32_e32 v192, 16, v193
	v_and_b32_e32 v193, 0xffff0000, v193
	v_pk_fma_f32 v[124:125], v[124:125], v[228:229], v[194:195]
	v_pk_fma_f32 v[192:193], v[122:123], v[120:121], v[192:193]
	v_cvt_pk_bf16_f32 v120, v124, v125
	v_cvt_pk_bf16_f32 v121, v126, v127
	v_cvt_pk_bf16_f32 v122, v190, v191
	v_cvt_pk_bf16_f32 v123, v192, v193
	global_store_dwordx4 v[170:171], v[120:123], off
	s_waitcnt vmcnt(8)
	v_lshlrev_b32_e32 v190, 16, v156
	v_lshlrev_b32_e32 v120, 16, v202
	v_and_b32_e32 v121, 0xffff0000, v202
	v_lshlrev_b32_e32 v122, 16, v206
	v_and_b32_e32 v123, 0xffff0000, v206
	v_pk_fma_f32 v[116:117], v[116:117], v[120:121], v[122:123]
	v_lshlrev_b32_e32 v120, 16, v203
	v_and_b32_e32 v121, 0xffff0000, v203
	v_lshlrev_b32_e32 v122, 16, v207
	v_and_b32_e32 v123, 0xffff0000, v207
	v_pk_fma_f32 v[118:119], v[118:119], v[120:121], v[122:123]
	v_lshlrev_b32_e32 v120, 16, v204
	v_and_b32_e32 v121, 0xffff0000, v204
	v_lshlrev_b32_e32 v122, 16, v208
	v_and_b32_e32 v123, 0xffff0000, v208
	v_pk_fma_f32 v[120:121], v[112:113], v[120:121], v[122:123]
	v_lshlrev_b32_e32 v112, 16, v205
	v_and_b32_e32 v113, 0xffff0000, v205
	v_lshlrev_b32_e32 v122, 16, v209
	v_and_b32_e32 v123, 0xffff0000, v209
	v_pk_fma_f32 v[122:123], v[114:115], v[112:113], v[122:123]
	v_cvt_pk_bf16_f32 v112, v116, v117
	v_cvt_pk_bf16_f32 v113, v118, v119
	v_cvt_pk_bf16_f32 v114, v120, v121
	v_cvt_pk_bf16_f32 v115, v122, v123
	global_store_dwordx4 v[170:171], v[112:115], off offset:256
	v_and_b32_e32 v191, 0xffff0000, v156
	s_waitcnt vmcnt(7)
;     __device__ __forceinline__ void operator()(const f32x4 (&acc)[2][2][4][2], const Unit& u, int wr, int wc, int fr, int fq) const {
;     ...
;         for (int ch = 0; ch <= 4; ++ch) {
;             if (ch < 4) {
; #pragma unroll
;                 for (int mm = 0; mm < 2; ++mm) { const size_t row = (size_t)(row0 + (ch >> 1) * HALF + ((ch & 1) * 2 + mm) * 16);
; #pragma unroll
;                     for (int bj = 0; bj < 2; ++bj) { const int c = col0 + bj * HALF;
;                         gw[ch & 1][mm][bj] = *(const u32x4*)(G + row * 4096 + (SECOND ? 2048 : 0) + c);
;                         if (SECOND) tw[ch & 1][mm][bj] = *(const u32x4*)(T + row * 2048 + c); } }
;             }
;             asm volatile("" ::: "memory");
;             if (ch > 0) {
;                 const int pc = ch - 1, ai = pc >> 1;
; #pragma unroll
;                 for (int mm = 0; mm < 2; ++mm) { const int m = (pc & 1) * 2 + mm; const size_t row = (size_t)(row0 + ai * HALF + m * 16);
; #pragma unroll
;                     for (int bj = 0; bj < 2; ++bj) { const int c = col0 + bj * HALF;
;                         const f32x4 a0 = acc[ai][bj][m][0], a1 = acc[ai][bj][m][1];
;                         float o[8];
; #pragma unroll
;                         for (int e = 0; e < 4; ++e) {
;                             const unsigned gwe = gw[pc & 1][mm][bj][e], twe = SECOND ? tw[pc & 1][mm][bj][e] : 0u;
;                             const float glo = __uint_as_float(gwe << 16), ghi = __uint_as_float(gwe & 0xffff0000u);
;                             const float tlo = __uint_as_float(twe << 16), thi = __uint_as_float(twe & 0xffff0000u);
;                             const float alo = (e < 2) ? a0[2 * e] : a1[2 * e - 4], ahi = (e < 2) ? a0[2 * e + 1] : a1[2 * e - 3];
;                             o[2 * e] = tlo + glo * alo; o[2 * e + 1] = thi + ghi * ahi;
;                         }
;                         u32x4 w; w.x = cvt_pk_bf16(o[0], o[1]); w.y = cvt_pk_bf16(o[2], o[3]); w.z = cvt_pk_bf16(o[4], o[5]); w.w = cvt_pk_bf16(o[6], o[7]);
;                         *(u32x4*)(T + row * 2048 + c) = w;
;                     } }
	v_lshlrev_b32_e32 v192, 16, v152
	v_lshlrev_b32_e32 v112, 16, v210
	v_and_b32_e32 v113, 0xffff0000, v210
	v_lshlrev_b32_e32 v114, 16, v214
	v_and_b32_e32 v115, 0xffff0000, v214
	v_pk_fma_f32 v[108:109], v[108:109], v[112:113], v[114:115]
	v_lshlrev_b32_e32 v112, 16, v211
	v_and_b32_e32 v113, 0xffff0000, v211
	v_lshlrev_b32_e32 v114, 16, v215
	v_and_b32_e32 v115, 0xffff0000, v215
	v_pk_fma_f32 v[110:111], v[110:111], v[112:113], v[114:115]
	v_lshlrev_b32_e32 v112, 16, v212
	v_and_b32_e32 v113, 0xffff0000, v212
	v_lshlrev_b32_e32 v114, 16, v216
	v_and_b32_e32 v115, 0xffff0000, v216
	v_pk_fma_f32 v[112:113], v[104:105], v[112:113], v[114:115]
	v_lshlrev_b32_e32 v104, 16, v213
	v_and_b32_e32 v105, 0xffff0000, v213
	v_lshlrev_b32_e32 v114, 16, v217
	v_and_b32_e32 v115, 0xffff0000, v217
	v_pk_fma_f32 v[114:115], v[106:107], v[104:105], v[114:115]
	v_cvt_pk_bf16_f32 v104, v108, v109
	v_cvt_pk_bf16_f32 v105, v110, v111
	v_cvt_pk_bf16_f32 v106, v112, v113
	v_cvt_pk_bf16_f32 v107, v114, v115
	global_store_dwordx4 v[174:175], v[104:107], off
	v_and_b32_e32 v193, 0xffff0000, v152
	v_lshlrev_b32_e32 v156, 16, v157
	v_lshlrev_b32_e32 v104, 16, v222
	v_and_b32_e32 v105, 0xffff0000, v222
	v_lshlrev_b32_e32 v106, 16, v218
	v_and_b32_e32 v107, 0xffff0000, v218
	v_pk_fma_f32 v[100:101], v[100:101], v[104:105], v[106:107]
	v_lshlrev_b32_e32 v104, 16, v223
	v_and_b32_e32 v105, 0xffff0000, v223
	v_lshlrev_b32_e32 v106, 16, v219
	v_and_b32_e32 v107, 0xffff0000, v219
	v_pk_fma_f32 v[102:103], v[102:103], v[104:105], v[106:107]
	v_lshlrev_b32_e32 v104, 16, v224
	v_and_b32_e32 v105, 0xffff0000, v224
	v_lshlrev_b32_e32 v106, 16, v220
	v_and_b32_e32 v107, 0xffff0000, v220
	v_pk_fma_f32 v[104:105], v[96:97], v[104:105], v[106:107]
	v_lshlrev_b32_e32 v96, 16, v225
	v_and_b32_e32 v97, 0xffff0000, v225
	v_lshlrev_b32_e32 v106, 16, v221
	v_and_b32_e32 v107, 0xffff0000, v221
	v_pk_fma_f32 v[106:107], v[98:99], v[96:97], v[106:107]
	v_cvt_pk_bf16_f32 v96, v100, v101
	v_cvt_pk_bf16_f32 v97, v102, v103
	v_cvt_pk_bf16_f32 v98, v104, v105
	v_cvt_pk_bf16_f32 v99, v106, v107
	global_store_dwordx4 v[174:175], v[96:99], off offset:256
	v_and_b32_e32 v157, 0xffff0000, v157
	v_lshlrev_b32_e32 v152, 16, v153
	v_add_u32_e32 v96, 0x80, v164
	v_ashrrev_i32_e32 v97, 31, v96
	v_lshlrev_b64 v[98:99], 13, v[96:97]
	v_lshl_add_u64 v[98:99], s[70:71], 0, v[98:99]
	v_lshlrev_b64 v[96:97], 12, v[96:97]
	v_lshl_add_u64 v[96:97], s[6:7], 0, v[96:97]
	v_lshl_add_u64 v[98:99], v[98:99], 0, v[166:167]
	v_lshl_add_u64 v[100:101], v[98:99], 0, s[14:15]
	v_add_co_u32_e32 v98, vcc, s57, v98
	v_lshl_add_u64 v[174:175], v[96:97], 0, v[166:167]
	v_add_u32_e32 v96, 0x90, v164
	v_addc_co_u32_e32 v99, vcc, 0, v99, vcc
	v_ashrrev_i32_e32 v97, 31, v96
	global_load_dwordx4 v[124:127], v234, s[70:71]
	global_load_dwordx4 v[116:119], v234, s[70:71] offset:1024
	global_load_dwordx4 v[120:123], v238, s[62:63]
	global_load_dwordx4 v[112:115], v238, s[62:63] offset:1024
	v_lshlrev_b64 v[98:99], 13, v[96:97]
	v_and_b32_e32 v153, 0xffff0000, v153
	v_lshl_add_u64 v[98:99], s[70:71], 0, v[98:99]
	v_pk_fma_f32 v[94:95], v[94:95], v[156:157], v[152:153]
	v_lshlrev_b32_e32 v152, 16, v158
	v_and_b32_e32 v153, 0xffff0000, v158
	v_lshlrev_b32_e32 v156, 16, v154
	v_and_b32_e32 v157, 0xffff0000, v154
	v_lshl_add_u64 v[98:99], v[98:99], 0, v[166:167]
	v_pk_fma_f32 v[152:153], v[88:89], v[152:153], v[156:157]
	v_lshlrev_b32_e32 v88, 16, v159
	v_and_b32_e32 v89, 0xffff0000, v159
	v_lshlrev_b32_e32 v154, 16, v155
	v_and_b32_e32 v155, 0xffff0000, v155
	v_lshlrev_b64 v[96:97], 12, v[96:97]
	v_lshl_add_u64 v[100:101], v[98:99], 0, s[14:15]
	v_add_co_u32_e32 v98, vcc, s57, v98
	v_pk_fma_f32 v[92:93], v[92:93], v[190:191], v[192:193]
	v_pk_fma_f32 v[154:155], v[90:91], v[88:89], v[154:155]
	v_lshl_add_u64 v[96:97], s[6:7], 0, v[96:97]
	v_addc_co_u32_e32 v99, vcc, 0, v99, vcc
	v_cvt_pk_bf16_f32 v88, v92, v93
	v_cvt_pk_bf16_f32 v89, v94, v95
	v_cvt_pk_bf16_f32 v90, v152, v153
	v_cvt_pk_bf16_f32 v91, v154, v155
	v_lshl_add_u64 v[170:171], v[96:97], 0, v[166:167]
	global_load_dwordx4 v[108:111], v234, s[70:71] offset:2048
	s_nop 0
	global_load_dwordx4 v[100:103], v234, s[70:71] offset:3072
	s_nop 0
	global_load_dwordx4 v[104:107], v238, s[62:63] offset:2048
	global_load_dwordx4 v[96:99], v238, s[62:63] offset:3072
	global_store_dwordx4 v[172:173], v[88:91], off
	s_nop 1
	v_lshlrev_b32_e32 v88, 16, v148
	v_and_b32_e32 v89, 0xffff0000, v148
	s_waitcnt vmcnt(17)
	v_lshlrev_b32_e32 v90, 16, v144
	v_and_b32_e32 v91, 0xffff0000, v144
	v_pk_fma_f32 v[84:85], v[84:85], v[88:89], v[90:91]
	v_lshlrev_b32_e32 v88, 16, v149
	v_and_b32_e32 v89, 0xffff0000, v149
	v_lshlrev_b32_e32 v90, 16, v145
	v_and_b32_e32 v91, 0xffff0000, v145
	v_pk_fma_f32 v[86:87], v[86:87], v[88:89], v[90:91]
	v_lshlrev_b32_e32 v88, 16, v150
	v_and_b32_e32 v89, 0xffff0000, v150
	v_lshlrev_b32_e32 v90, 16, v146
	v_and_b32_e32 v91, 0xffff0000, v146
	v_pk_fma_f32 v[88:89], v[80:81], v[88:89], v[90:91]
	v_lshlrev_b32_e32 v80, 16, v151
	v_and_b32_e32 v81, 0xffff0000, v151
	v_lshlrev_b32_e32 v90, 16, v147
	v_and_b32_e32 v91, 0xffff0000, v147
	v_pk_fma_f32 v[90:91], v[82:83], v[80:81], v[90:91]
	v_cvt_pk_bf16_f32 v80, v84, v85
	v_cvt_pk_bf16_f32 v81, v86, v87
	v_cvt_pk_bf16_f32 v82, v88, v89
	v_cvt_pk_bf16_f32 v83, v90, v91
	global_store_dwordx4 v[172:173], v[80:83], off offset:256
	s_waitcnt vmcnt(17)
	s_nop 0
	v_lshlrev_b32_e32 v80, 16, v140
	v_and_b32_e32 v81, 0xffff0000, v140
	s_waitcnt vmcnt(15)
;     __device__ __forceinline__ void operator()(const f32x4 (&acc)[2][2][4][2], const Unit& u, int wr, int wc, int fr, int fq) const {
;     ...
;         for (int ch = 0; ch <= 4; ++ch) {
;             if (ch < 4) {
; #pragma unroll
;                 for (int mm = 0; mm < 2; ++mm) { const size_t row = (size_t)(row0 + (ch >> 1) * HALF + ((ch & 1) * 2 + mm) * 16);
; #pragma unroll
;                     for (int bj = 0; bj < 2; ++bj) { const int c = col0 + bj * HALF;
;                         gw[ch & 1][mm][bj] = *(const u32x4*)(G + row * 4096 + (SECOND ? 2048 : 0) + c);
;                         if (SECOND) tw[ch & 1][mm][bj] = *(const u32x4*)(T + row * 2048 + c); } }
;             }
;             asm volatile("" ::: "memory");
;             if (ch > 0) {
;                 const int pc = ch - 1, ai = pc >> 1;
; #pragma unroll
;                 for (int mm = 0; mm < 2; ++mm) { const int m = (pc & 1) * 2 + mm; const size_t row = (size_t)(row0 + ai * HALF + m * 16);
; #pragma unroll
;                     for (int bj = 0; bj < 2; ++bj) { const int c = col0 + bj * HALF;
;                         const f32x4 a0 = acc[ai][bj][m][0], a1 = acc[ai][bj][m][1];
;                         float o[8];
; #pragma unroll
;                         for (int e = 0; e < 4; ++e) {
;                             const unsigned gwe = gw[pc & 1][mm][bj][e], twe = SECOND ? tw[pc & 1][mm][bj][e] : 0u;
;                             const float glo = __uint_as_float(gwe << 16), ghi = __uint_as_float(gwe & 0xffff0000u);
;                             const float tlo = __uint_as_float(twe << 16), thi = __uint_as_float(twe & 0xffff0000u);
;                             const float alo = (e < 2) ? a0[2 * e] : a1[2 * e - 4], ahi = (e < 2) ? a0[2 * e + 1] : a1[2 * e - 3];
;                             o[2 * e] = tlo + glo * alo; o[2 * e + 1] = thi + ghi * ahi;
;                         }
;                         u32x4 w; w.x = cvt_pk_bf16(o[0], o[1]); w.y = cvt_pk_bf16(o[2], o[3]); w.z = cvt_pk_bf16(o[4], o[5]); w.w = cvt_pk_bf16(o[6], o[7]);
;                         *(u32x4*)(T + row * 2048 + c) = w;
;                     } }
	v_lshlrev_b32_e32 v82, 16, v136
	v_and_b32_e32 v83, 0xffff0000, v136
	v_pk_fma_f32 v[76:77], v[76:77], v[80:81], v[82:83]
	v_lshlrev_b32_e32 v80, 16, v141
	v_and_b32_e32 v81, 0xffff0000, v141
	v_lshlrev_b32_e32 v82, 16, v137
	v_and_b32_e32 v83, 0xffff0000, v137
	v_pk_fma_f32 v[78:79], v[78:79], v[80:81], v[82:83]
	v_lshlrev_b32_e32 v80, 16, v142
	v_and_b32_e32 v81, 0xffff0000, v142
	v_lshlrev_b32_e32 v82, 16, v138
	v_and_b32_e32 v83, 0xffff0000, v138
	v_pk_fma_f32 v[80:81], v[72:73], v[80:81], v[82:83]
	v_lshlrev_b32_e32 v72, 16, v143
	v_and_b32_e32 v73, 0xffff0000, v143
	v_lshlrev_b32_e32 v82, 16, v139
	v_and_b32_e32 v83, 0xffff0000, v139
	v_pk_fma_f32 v[82:83], v[74:75], v[72:73], v[82:83]
	v_cvt_pk_bf16_f32 v72, v76, v77
	v_cvt_pk_bf16_f32 v73, v78, v79
	v_cvt_pk_bf16_f32 v74, v80, v81
	v_cvt_pk_bf16_f32 v75, v82, v83
	global_store_dwordx4 v[168:169], v[72:75], off
	s_nop 1
	v_lshlrev_b32_e32 v72, 16, v132
	v_and_b32_e32 v73, 0xffff0000, v132
	s_waitcnt vmcnt(15)
	v_lshlrev_b32_e32 v74, 16, v128
	v_and_b32_e32 v75, 0xffff0000, v128
	v_pk_fma_f32 v[68:69], v[68:69], v[72:73], v[74:75]
	v_lshlrev_b32_e32 v72, 16, v133
	v_and_b32_e32 v73, 0xffff0000, v133
	v_lshlrev_b32_e32 v74, 16, v129
	v_and_b32_e32 v75, 0xffff0000, v129
	v_pk_fma_f32 v[70:71], v[70:71], v[72:73], v[74:75]
	v_lshlrev_b32_e32 v72, 16, v134
	v_and_b32_e32 v73, 0xffff0000, v134
	v_lshlrev_b32_e32 v74, 16, v130
	v_and_b32_e32 v75, 0xffff0000, v130
	v_pk_fma_f32 v[72:73], v[64:65], v[72:73], v[74:75]
	v_lshlrev_b32_e32 v64, 16, v135
	v_and_b32_e32 v65, 0xffff0000, v135
	v_lshlrev_b32_e32 v74, 16, v131
	v_and_b32_e32 v75, 0xffff0000, v131
	v_pk_fma_f32 v[74:75], v[66:67], v[64:65], v[74:75]
	v_cvt_pk_bf16_f32 v64, v68, v69
	v_cvt_pk_bf16_f32 v65, v70, v71
	v_cvt_pk_bf16_f32 v66, v72, v73
	v_cvt_pk_bf16_f32 v67, v74, v75
	global_store_dwordx4 v[168:169], v[64:67], off offset:256
	s_waitcnt vmcnt(11)
	v_lshlrev_b32_e32 v132, 16, v124
	v_and_b32_e32 v133, 0xffff0000, v124
	v_add_u32_e32 v64, 0xa0, v164
	v_ashrrev_i32_e32 v65, 31, v64
	v_lshlrev_b64 v[66:67], 13, v[64:65]
	v_lshl_add_u64 v[66:67], s[70:71], 0, v[66:67]
	v_lshl_add_u64 v[66:67], v[66:67], 0, v[166:167]
	v_lshlrev_b64 v[64:65], 12, v[64:65]
	v_lshl_add_u64 v[68:69], v[66:67], 0, s[14:15]
	v_add_co_u32_e32 v66, vcc, s57, v66
	v_lshl_add_u64 v[64:65], s[6:7], 0, v[64:65]
	s_nop 0
	v_addc_co_u32_e32 v67, vcc, 0, v67, vcc
	v_lshl_add_u64 v[130:131], v[64:65], 0, v[166:167]
	global_load_dwordx4 v[92:95], v235, s[70:71]
	global_load_dwordx4 v[84:87], v235, s[70:71] offset:1024
	global_load_dwordx4 v[88:91], v239, s[62:63]
	global_load_dwordx4 v[80:83], v239, s[62:63] offset:1024
	v_add_u32_e32 v64, 0xb0, v164
	v_ashrrev_i32_e32 v65, 31, v64
	v_lshlrev_b64 v[66:67], 13, v[64:65]
	v_lshl_add_u64 v[66:67], s[70:71], 0, v[66:67]
	v_lshl_add_u64 v[66:67], v[66:67], 0, v[166:167]
	v_lshlrev_b64 v[64:65], 12, v[64:65]
	v_lshl_add_u64 v[68:69], v[66:67], 0, s[14:15]
	v_add_co_u32_e32 v66, vcc, s57, v66
	v_lshl_add_u64 v[64:65], s[6:7], 0, v[64:65]
	s_nop 0
	v_addc_co_u32_e32 v67, vcc, 0, v67, vcc
	v_lshl_add_u64 v[128:129], v[64:65], 0, v[166:167]
	global_load_dwordx4 v[76:79], v235, s[70:71] offset:2048
	s_nop 0
	global_load_dwordx4 v[68:71], v235, s[70:71] offset:3072
	s_nop 0
	global_load_dwordx4 v[72:75], v239, s[62:63] offset:2048
	global_load_dwordx4 v[64:67], v239, s[62:63] offset:3072
	s_waitcnt vmcnt(17)
	v_lshlrev_b32_e32 v134, 16, v120
	v_and_b32_e32 v135, 0xffff0000, v120
	v_lshlrev_b32_e32 v124, 16, v125
	v_and_b32_e32 v125, 0xffff0000, v125
	v_lshlrev_b32_e32 v120, 16, v121
	v_and_b32_e32 v121, 0xffff0000, v121
	v_pk_fma_f32 v[62:63], v[62:63], v[124:125], v[120:121]
	v_lshlrev_b32_e32 v120, 16, v126
	v_and_b32_e32 v121, 0xffff0000, v126
	v_lshlrev_b32_e32 v124, 16, v122
	v_and_b32_e32 v125, 0xffff0000, v122
	v_pk_fma_f32 v[120:121], v[56:57], v[120:121], v[124:125]
	v_lshlrev_b32_e32 v56, 16, v127
	v_and_b32_e32 v57, 0xffff0000, v127
	v_lshlrev_b32_e32 v122, 16, v123
	v_and_b32_e32 v123, 0xffff0000, v123
	v_pk_fma_f32 v[60:61], v[60:61], v[132:133], v[134:135]
	v_pk_fma_f32 v[122:123], v[58:59], v[56:57], v[122:123]
	v_cvt_pk_bf16_f32 v56, v60, v61
	v_cvt_pk_bf16_f32 v57, v62, v63
	v_cvt_pk_bf16_f32 v58, v120, v121
	v_cvt_pk_bf16_f32 v59, v122, v123
	global_store_dwordx4 v[174:175], v[56:59], off
	s_andn2_b64 vcc, exec, s[0:1]
	s_mov_b64 s[0:1], -1
	v_lshlrev_b32_e32 v56, 16, v116
	v_and_b32_e32 v57, 0xffff0000, v116
	s_waitcnt vmcnt(17)
	v_lshlrev_b32_e32 v58, 16, v112
	v_and_b32_e32 v59, 0xffff0000, v112
	v_pk_fma_f32 v[52:53], v[52:53], v[56:57], v[58:59]
	v_lshlrev_b32_e32 v56, 16, v117
	v_and_b32_e32 v57, 0xffff0000, v117
	v_lshlrev_b32_e32 v58, 16, v113
	v_and_b32_e32 v59, 0xffff0000, v113
	v_pk_fma_f32 v[54:55], v[54:55], v[56:57], v[58:59]
	v_lshlrev_b32_e32 v56, 16, v118
	v_and_b32_e32 v57, 0xffff0000, v118
	v_lshlrev_b32_e32 v58, 16, v114
	v_and_b32_e32 v59, 0xffff0000, v114
	v_pk_fma_f32 v[56:57], v[48:49], v[56:57], v[58:59]
	v_lshlrev_b32_e32 v48, 16, v119
	v_and_b32_e32 v49, 0xffff0000, v119
	v_lshlrev_b32_e32 v58, 16, v115
	v_and_b32_e32 v59, 0xffff0000, v115
	v_pk_fma_f32 v[58:59], v[50:51], v[48:49], v[58:59]
	v_cvt_pk_bf16_f32 v48, v52, v53
	v_cvt_pk_bf16_f32 v49, v54, v55
	v_cvt_pk_bf16_f32 v50, v56, v57
	v_cvt_pk_bf16_f32 v51, v58, v59
	global_store_dwordx4 v[174:175], v[48:51], off offset:256
	s_waitcnt vmcnt(17)
	s_nop 0
	v_lshlrev_b32_e32 v48, 16, v108
	v_and_b32_e32 v49, 0xffff0000, v108
	s_waitcnt vmcnt(15)
; __device__ __forceinline__ unsigned cvt_pk_bf16(float lo, float hi) { typedef float f2_t __attribute__((ext_vector_type(2))); typedef __bf16 b2_t __attribute__((ext_vector_type(2))); const f2_t v = {lo, hi}; return __builtin_bit_cast(unsigned, __builtin_convertvector(v, b2_t)); }
; #define PG8_BAR __builtin_amdgcn_s_barrier()
; template <class Epi, class Sched, bool ALIGN_EPI = false, bool SP2 = false>
; __device__ __forceinline__ void gemm_phase(PG8_LAS unsigned char* lds, const Gemm g, const Sched& S, const Epi& E) {
;     ...
;         if (!has_next) break;
;         cur = nxt; cA = nA; cB = nB; ++ui;
;         if constexpr (ALIGN_EPI) { if (wr == 1) PG8_BAR; }
;     __device__ __forceinline__ void operator()(const f32x4 (&acc)[2][2][4][2], const Unit& u, int wr, int wc, int fr, int fq) const {
;     ...
;             if (ch > 0) {
;                 const int pc = ch - 1, ai = pc >> 1;
; #pragma unroll
;                 for (int mm = 0; mm < 2; ++mm) { const int m = (pc & 1) * 2 + mm; const size_t row = (size_t)(row0 + ai * HALF + m * 16);
; #pragma unroll
;                     for (int bj = 0; bj < 2; ++bj) { const int c = col0 + bj * HALF;
;                         const f32x4 a0 = acc[ai][bj][m][0], a1 = acc[ai][bj][m][1];
;                         float o[8];
; #pragma unroll
;                         for (int e = 0; e < 4; ++e) {
;                             const unsigned gwe = gw[pc & 1][mm][bj][e], twe = SECOND ? tw[pc & 1][mm][bj][e] : 0u;
;                             const float glo = __uint_as_float(gwe << 16), ghi = __uint_as_float(gwe & 0xffff0000u);
;                             const float tlo = __uint_as_float(twe << 16), thi = __uint_as_float(twe & 0xffff0000u);
;                             const float alo = (e < 2) ? a0[2 * e] : a1[2 * e - 4], ahi = (e < 2) ? a0[2 * e + 1] : a1[2 * e - 3];
;                             o[2 * e] = tlo + glo * alo; o[2 * e + 1] = thi + ghi * ahi;
;                         }
;                         u32x4 w; w.x = cvt_pk_bf16(o[0], o[1]); w.y = cvt_pk_bf16(o[2], o[3]); w.z = cvt_pk_bf16(o[4], o[5]); w.w = cvt_pk_bf16(o[6], o[7]);
;                         *(u32x4*)(T + row * 2048 + c) = w;
;                     } }
	v_lshlrev_b32_e32 v50, 16, v104
	v_and_b32_e32 v51, 0xffff0000, v104
	v_pk_fma_f32 v[44:45], v[44:45], v[48:49], v[50:51]
	v_lshlrev_b32_e32 v48, 16, v109
	v_and_b32_e32 v49, 0xffff0000, v109
	v_lshlrev_b32_e32 v50, 16, v105
	v_and_b32_e32 v51, 0xffff0000, v105
	v_pk_fma_f32 v[46:47], v[46:47], v[48:49], v[50:51]
	v_lshlrev_b32_e32 v48, 16, v110
	v_and_b32_e32 v49, 0xffff0000, v110
	v_lshlrev_b32_e32 v50, 16, v106
	v_and_b32_e32 v51, 0xffff0000, v106
	v_pk_fma_f32 v[48:49], v[40:41], v[48:49], v[50:51]
	v_lshlrev_b32_e32 v40, 16, v111
	v_and_b32_e32 v41, 0xffff0000, v111
	v_lshlrev_b32_e32 v50, 16, v107
	v_and_b32_e32 v51, 0xffff0000, v107
	v_pk_fma_f32 v[50:51], v[42:43], v[40:41], v[50:51]
	v_cvt_pk_bf16_f32 v40, v44, v45
	v_cvt_pk_bf16_f32 v41, v46, v47
	v_cvt_pk_bf16_f32 v42, v48, v49
	v_cvt_pk_bf16_f32 v43, v50, v51
	global_store_dwordx4 v[170:171], v[40:43], off
	s_nop 1
	v_lshlrev_b32_e32 v40, 16, v100
	v_and_b32_e32 v41, 0xffff0000, v100
	s_waitcnt vmcnt(15)
	v_lshlrev_b32_e32 v42, 16, v96
	v_and_b32_e32 v43, 0xffff0000, v96
	v_pk_fma_f32 v[36:37], v[36:37], v[40:41], v[42:43]
	v_lshlrev_b32_e32 v40, 16, v101
	v_and_b32_e32 v41, 0xffff0000, v101
	v_lshlrev_b32_e32 v42, 16, v97
	v_and_b32_e32 v43, 0xffff0000, v97
	v_pk_fma_f32 v[38:39], v[38:39], v[40:41], v[42:43]
	v_lshlrev_b32_e32 v40, 16, v102
	v_and_b32_e32 v41, 0xffff0000, v102
	v_lshlrev_b32_e32 v42, 16, v98
	v_and_b32_e32 v43, 0xffff0000, v98
	v_pk_fma_f32 v[40:41], v[32:33], v[40:41], v[42:43]
	v_lshlrev_b32_e32 v32, 16, v103
	v_and_b32_e32 v33, 0xffff0000, v103
	v_lshlrev_b32_e32 v42, 16, v99
	v_and_b32_e32 v43, 0xffff0000, v99
	v_pk_fma_f32 v[42:43], v[34:35], v[32:33], v[42:43]
	v_cvt_pk_bf16_f32 v32, v36, v37
	v_cvt_pk_bf16_f32 v33, v38, v39
	v_cvt_pk_bf16_f32 v34, v40, v41
	v_cvt_pk_bf16_f32 v35, v42, v43
	global_store_dwordx4 v[170:171], v[32:35], off offset:256
	s_waitcnt vmcnt(11)
	s_nop 0
	v_lshlrev_b32_e32 v32, 16, v92
	v_and_b32_e32 v33, 0xffff0000, v92
	s_waitcnt vmcnt(9)
	v_lshlrev_b32_e32 v34, 16, v88
	v_and_b32_e32 v35, 0xffff0000, v88
	v_pk_fma_f32 v[28:29], v[28:29], v[32:33], v[34:35]
	v_lshlrev_b32_e32 v32, 16, v93
	v_and_b32_e32 v33, 0xffff0000, v93
	v_lshlrev_b32_e32 v34, 16, v89
	v_and_b32_e32 v35, 0xffff0000, v89
	v_pk_fma_f32 v[30:31], v[30:31], v[32:33], v[34:35]
	v_lshlrev_b32_e32 v32, 16, v94
	v_and_b32_e32 v33, 0xffff0000, v94
	v_lshlrev_b32_e32 v34, 16, v90
	v_and_b32_e32 v35, 0xffff0000, v90
	v_pk_fma_f32 v[32:33], v[24:25], v[32:33], v[34:35]
	v_lshlrev_b32_e32 v24, 16, v95
	v_and_b32_e32 v25, 0xffff0000, v95
	v_lshlrev_b32_e32 v34, 16, v91
	v_and_b32_e32 v35, 0xffff0000, v91
	v_pk_fma_f32 v[34:35], v[26:27], v[24:25], v[34:35]
	v_cvt_pk_bf16_f32 v24, v28, v29
	v_cvt_pk_bf16_f32 v25, v30, v31
	v_cvt_pk_bf16_f32 v26, v32, v33
	v_cvt_pk_bf16_f32 v27, v34, v35
	global_store_dwordx4 v[130:131], v[24:27], off
	s_nop 1
	v_lshlrev_b32_e32 v24, 16, v84
	v_and_b32_e32 v25, 0xffff0000, v84
	s_waitcnt vmcnt(9)
	v_lshlrev_b32_e32 v26, 16, v80
	v_and_b32_e32 v27, 0xffff0000, v80
	v_pk_fma_f32 v[20:21], v[20:21], v[24:25], v[26:27]
	v_lshlrev_b32_e32 v24, 16, v85
	v_and_b32_e32 v25, 0xffff0000, v85
	v_lshlrev_b32_e32 v26, 16, v81
	v_and_b32_e32 v27, 0xffff0000, v81
	v_pk_fma_f32 v[22:23], v[22:23], v[24:25], v[26:27]
	v_lshlrev_b32_e32 v24, 16, v86
	v_and_b32_e32 v25, 0xffff0000, v86
	v_lshlrev_b32_e32 v26, 16, v82
	v_and_b32_e32 v27, 0xffff0000, v82
	v_pk_fma_f32 v[24:25], v[16:17], v[24:25], v[26:27]
	v_lshlrev_b32_e32 v16, 16, v87
	v_and_b32_e32 v17, 0xffff0000, v87
	v_lshlrev_b32_e32 v26, 16, v83
	v_and_b32_e32 v27, 0xffff0000, v83
	v_pk_fma_f32 v[26:27], v[18:19], v[16:17], v[26:27]
	v_cvt_pk_bf16_f32 v16, v20, v21
	v_cvt_pk_bf16_f32 v17, v22, v23
	v_cvt_pk_bf16_f32 v18, v24, v25
	v_cvt_pk_bf16_f32 v19, v26, v27
	global_store_dwordx4 v[130:131], v[16:19], off offset:256
	s_waitcnt vmcnt(9)
	s_nop 0
	v_lshlrev_b32_e32 v16, 16, v76
	v_and_b32_e32 v17, 0xffff0000, v76
	s_waitcnt vmcnt(7)
	v_lshlrev_b32_e32 v18, 16, v72
	v_and_b32_e32 v19, 0xffff0000, v72
	v_pk_fma_f32 v[12:13], v[12:13], v[16:17], v[18:19]
	v_lshlrev_b32_e32 v16, 16, v77
	v_and_b32_e32 v17, 0xffff0000, v77
	v_lshlrev_b32_e32 v18, 16, v73
	v_and_b32_e32 v19, 0xffff0000, v73
	v_pk_fma_f32 v[14:15], v[14:15], v[16:17], v[18:19]
	v_lshlrev_b32_e32 v16, 16, v78
	v_and_b32_e32 v17, 0xffff0000, v78
	v_lshlrev_b32_e32 v18, 16, v74
	v_and_b32_e32 v19, 0xffff0000, v74
	v_pk_fma_f32 v[16:17], v[8:9], v[16:17], v[18:19]
	v_lshlrev_b32_e32 v8, 16, v79
	v_and_b32_e32 v9, 0xffff0000, v79
	v_lshlrev_b32_e32 v18, 16, v75
	v_and_b32_e32 v19, 0xffff0000, v75
	v_pk_fma_f32 v[18:19], v[10:11], v[8:9], v[18:19]
	v_cvt_pk_bf16_f32 v8, v12, v13
	v_cvt_pk_bf16_f32 v9, v14, v15
	v_cvt_pk_bf16_f32 v10, v16, v17
	v_cvt_pk_bf16_f32 v11, v18, v19
	global_store_dwordx4 v[128:129], v[8:11], off
	s_nop 1
	v_lshlrev_b32_e32 v8, 16, v68
	v_and_b32_e32 v9, 0xffff0000, v68
	s_waitcnt vmcnt(7)
	v_lshlrev_b32_e32 v10, 16, v64
	v_and_b32_e32 v11, 0xffff0000, v64
	v_pk_fma_f32 v[4:5], v[4:5], v[8:9], v[10:11]
	v_lshlrev_b32_e32 v8, 16, v69
	v_and_b32_e32 v9, 0xffff0000, v69
	v_lshlrev_b32_e32 v10, 16, v65
	v_and_b32_e32 v11, 0xffff0000, v65
	v_pk_fma_f32 v[6:7], v[6:7], v[8:9], v[10:11]
	v_lshlrev_b32_e32 v8, 16, v70
	v_and_b32_e32 v9, 0xffff0000, v70
	v_lshlrev_b32_e32 v10, 16, v66
	v_and_b32_e32 v11, 0xffff0000, v66
	v_pk_fma_f32 v[8:9], v[0:1], v[8:9], v[10:11]
	v_lshlrev_b32_e32 v0, 16, v71
	v_and_b32_e32 v1, 0xffff0000, v71
	v_lshlrev_b32_e32 v10, 16, v67
	v_and_b32_e32 v11, 0xffff0000, v67
	v_pk_fma_f32 v[10:11], v[2:3], v[0:1], v[10:11]
	v_cvt_pk_bf16_f32 v0, v4, v5
	v_cvt_pk_bf16_f32 v1, v6, v7
	v_cvt_pk_bf16_f32 v2, v8, v9
	v_cvt_pk_bf16_f32 v3, v10, v11
	global_store_dwordx4 v[128:129], v[0:3], off offset:256
	s_cbranch_vccnz .LBB0_498
	s_andn2_b64 vcc, exec, s[10:11]
	s_cbranch_vccnz .LBB0_497
	s_barrier
	s_branch .LBB0_497
